# c10: in-proj elementwise epilogue specialised per mode (raw / silu / sigmoid+bias) instead of per-fragment mode tests
# speedup vs baseline: 1.0422x; 1.0062x over previous
; __device__ __forceinline__ float siluf(float v) { return v * __builtin_amdgcn_rcpf(1.f + __builtin_amdgcn_exp2f(-1.4426950408889634f * v)); }
; __device__ __forceinline__ float sigmf(float v) { return __builtin_amdgcn_rcpf(1.f + __builtin_amdgcn_exp2f(-1.4426950408889634f * v)); }
; #define G1_STG(mi_, ni_, v_) do { const int r_ = (mi_) * 16 + idx; const f32x4 t_ = (v_); u32x2 pk_; pk_.x = pk2(t_.x, t_.y); pk_.y = pk2(t_.z, t_.w); \
;         *(u32x2*)(wl + r_ * 128 + ((((ni_) * 2 + (kq >> 1)) ^ (r_ & 7)) * 16) + (kq & 1) * 8) = pk_; } while (0)
; __device__ void gemm1_phase(const Params& p, int l, int hb, unsigned char* smem) {
;     ...
;             int mode;
;             if (cw < 768) { dbase = (bf16_t*)(p.ws + WS_VA); dpitch = 128; dc0 = cw - 640; mode = 0; }
;             else if (cw < 1280) { dbase = (bf16_t*)(p.ws + WS_GA); dpitch = 512; dc0 = cw - 768; mode = 1; }
;             else if (cw < 3840) { dbase = (bf16_t*)(p.ws + WS_GB); dpitch = 256; dc0 = cw - 3584; mode = 1; }
;             else if (cw < 4864) { dbase = (bf16_t*)(p.ws + WS_XBC); dpitch = 1024; dc0 = cw - 3840; mode = 0; }
;             else if (cw < 5376) { dbase = (bf16_t*)(p.ws + WS_ZS); dpitch = 512; dc0 = cw - 4864; mode = 1; }
;             else { dbase = (bf16_t*)(p.ws + WS_MG); dpitch = 3072; dc0 = cw - 5376; mode = 2; }
;             const float* bg = p.b_gate + l * 3072 + dc0 + lc;
; #pragma unroll
;             for (int mi = 0; mi < 8; ++mi) {
; #pragma unroll
;                 for (int ni = 0; ni < 4; ++ni) {
;                     f32x4 v = acc[mi][ni];
;                     if (mode == 1) { v.x = siluf(v.x); v.y = siluf(v.y); v.z = siluf(v.z); v.w = siluf(v.w); }
;                     else if (mode == 2) { const f32x4 bb = *(const f32x4*)(bg + ni * 16); v.x = sigmf(v.x + bb.x); v.y = sigmf(v.y + bb.y); v.z = sigmf(v.z + bb.z); v.w = sigmf(v.w + bb.w); }
;                     G1_STG(mi, ni, v);
;                 }
;             }
.LBB0_271:
	s_add_i32 s58, s9, s54
	s_ashr_i32 s59, s58, 31
	s_xor_b64 s[62:63], s[38:39], -1
	s_lshl_b64 s[16:17], s[58:59], 2
	s_add_u32 s16, s25, s16
	s_addc_u32 s17, s51, s17
	v_lshlrev_b32_e32 v80, 2, v157
	v_lshl_add_u64 v[130:131], s[16:17], 0, v[80:81]
	global_load_dwordx4 v[160:163], v[130:131], off
	global_load_dwordx4 v[164:167], v[130:131], off offset:64
	global_load_dwordx4 v[168:171], v[130:131], off offset:128
	global_load_dwordx4 v[172:175], v[130:131], off offset:192
	v_readlane_b32 s66, v255, 56
	v_readlane_b32 s67, v255, 57
	v_lshlrev_b32_e32 v130, 7, v231
	v_and_b32_e32 v131, 1, v156
	v_lshl_add_u32 v130, v131, 3, v130
	v_add_u32_e32 v130, s61, v130
	v_lshrrev_b32_e32 v131, 1, v156
	v_and_b32_e32 v132, 7, v231
	v_or_b32_e32 v133, 0, v131
	v_xor_b32_e32 v133, v133, v132
	v_lshl_add_u32 v136, v133, 4, v130
	v_or_b32_e32 v133, 2, v131
	v_xor_b32_e32 v133, v133, v132
	v_lshl_add_u32 v137, v133, 4, v130
	v_or_b32_e32 v133, 4, v131
	v_xor_b32_e32 v133, v133, v132
	v_lshl_add_u32 v138, v133, 4, v130
	v_or_b32_e32 v133, 6, v131
	v_xor_b32_e32 v133, v133, v132
	v_lshl_add_u32 v139, v133, 4, v130
	s_and_b64 vcc, exec, s[36:37]
	s_cbranch_vccnz .Lg1e_sig
	s_and_b64 vcc, exec, s[38:39]
	s_cbranch_vccnz .Lg1e_silu
	v_cvt_pk_bf16_f32 v126, v126, v127
	v_cvt_pk_bf16_f32 v127, v128, v129
	ds_write_b64 v136, v[126:127]
	v_cvt_pk_bf16_f32 v122, v122, v123
	v_cvt_pk_bf16_f32 v123, v124, v125
	ds_write_b64 v137, v[122:123]
	v_cvt_pk_bf16_f32 v118, v118, v119
	v_cvt_pk_bf16_f32 v119, v120, v121
	ds_write_b64 v138, v[118:119]
	v_cvt_pk_bf16_f32 v114, v114, v115
	v_cvt_pk_bf16_f32 v115, v116, v117
	ds_write_b64 v139, v[114:115]
	v_cvt_pk_bf16_f32 v110, v110, v111
	v_cvt_pk_bf16_f32 v111, v112, v113
	ds_write_b64 v136, v[110:111] offset:2048
	v_cvt_pk_bf16_f32 v106, v106, v107
	v_cvt_pk_bf16_f32 v107, v108, v109
	ds_write_b64 v137, v[106:107] offset:2048
	v_cvt_pk_bf16_f32 v102, v102, v103
	v_cvt_pk_bf16_f32 v103, v104, v105
	ds_write_b64 v138, v[102:103] offset:2048
	v_cvt_pk_bf16_f32 v98, v98, v99
	v_cvt_pk_bf16_f32 v99, v100, v101
	ds_write_b64 v139, v[98:99] offset:2048
	v_cvt_pk_bf16_f32 v94, v94, v95
	v_cvt_pk_bf16_f32 v95, v96, v97
	ds_write_b64 v136, v[94:95] offset:4096
	v_cvt_pk_bf16_f32 v90, v90, v91
	v_cvt_pk_bf16_f32 v91, v92, v93
	ds_write_b64 v137, v[90:91] offset:4096
	v_cvt_pk_bf16_f32 v86, v86, v87
	v_cvt_pk_bf16_f32 v87, v88, v89
	ds_write_b64 v138, v[86:87] offset:4096
	v_cvt_pk_bf16_f32 v82, v82, v83
	v_cvt_pk_bf16_f32 v83, v84, v85
	ds_write_b64 v139, v[82:83] offset:4096
	v_cvt_pk_bf16_f32 v76, v76, v77
	v_cvt_pk_bf16_f32 v77, v78, v79
	ds_write_b64 v136, v[76:77] offset:6144
	v_cvt_pk_bf16_f32 v72, v72, v73
	v_cvt_pk_bf16_f32 v73, v74, v75
	ds_write_b64 v137, v[72:73] offset:6144
	v_cvt_pk_bf16_f32 v68, v68, v69
	v_cvt_pk_bf16_f32 v69, v70, v71
	ds_write_b64 v138, v[68:69] offset:6144
	v_cvt_pk_bf16_f32 v64, v64, v65
	v_cvt_pk_bf16_f32 v65, v66, v67
	ds_write_b64 v139, v[64:65] offset:6144
	v_cvt_pk_bf16_f32 v60, v60, v61
	v_cvt_pk_bf16_f32 v61, v62, v63
	ds_write_b64 v136, v[60:61] offset:8192
	v_cvt_pk_bf16_f32 v56, v56, v57
	v_cvt_pk_bf16_f32 v57, v58, v59
	ds_write_b64 v137, v[56:57] offset:8192
	v_cvt_pk_bf16_f32 v52, v52, v53
	v_cvt_pk_bf16_f32 v53, v54, v55
	ds_write_b64 v138, v[52:53] offset:8192
	v_cvt_pk_bf16_f32 v48, v48, v49
	v_cvt_pk_bf16_f32 v49, v50, v51
	ds_write_b64 v139, v[48:49] offset:8192
	v_cvt_pk_bf16_f32 v44, v44, v45
	v_cvt_pk_bf16_f32 v45, v46, v47
	ds_write_b64 v136, v[44:45] offset:10240
	v_cvt_pk_bf16_f32 v40, v40, v41
	v_cvt_pk_bf16_f32 v41, v42, v43
	ds_write_b64 v137, v[40:41] offset:10240
	v_cvt_pk_bf16_f32 v36, v36, v37
	v_cvt_pk_bf16_f32 v37, v38, v39
	ds_write_b64 v138, v[36:37] offset:10240
	v_cvt_pk_bf16_f32 v32, v32, v33
	v_cvt_pk_bf16_f32 v33, v34, v35
	ds_write_b64 v139, v[32:33] offset:10240
	v_cvt_pk_bf16_f32 v28, v28, v29
	v_cvt_pk_bf16_f32 v29, v30, v31
	ds_write_b64 v136, v[28:29] offset:12288
	v_cvt_pk_bf16_f32 v24, v24, v25
	v_cvt_pk_bf16_f32 v25, v26, v27
	ds_write_b64 v137, v[24:25] offset:12288
	v_cvt_pk_bf16_f32 v20, v20, v21
	v_cvt_pk_bf16_f32 v21, v22, v23
	ds_write_b64 v138, v[20:21] offset:12288
	v_cvt_pk_bf16_f32 v16, v16, v17
	v_cvt_pk_bf16_f32 v17, v18, v19
	ds_write_b64 v139, v[16:17] offset:12288
	v_cvt_pk_bf16_f32 v12, v12, v13
	v_cvt_pk_bf16_f32 v13, v14, v15
	ds_write_b64 v136, v[12:13] offset:14336
	v_cvt_pk_bf16_f32 v8, v8, v9
	v_cvt_pk_bf16_f32 v9, v10, v11
	ds_write_b64 v137, v[8:9] offset:14336
	v_cvt_pk_bf16_f32 v4, v4, v5
	v_cvt_pk_bf16_f32 v5, v6, v7
	ds_write_b64 v138, v[4:5] offset:14336
	v_cvt_pk_bf16_f32 v0, v0, v1
	v_cvt_pk_bf16_f32 v1, v2, v3
	ds_write_b64 v139, v[0:1] offset:14336
	s_branch .Lg1e_done
; __device__ __forceinline__ float sigmf(float v) { return __builtin_amdgcn_rcpf(1.f + __builtin_amdgcn_exp2f(-1.4426950408889634f * v)); }
; #define G1_STG(mi_, ni_, v_) do { const int r_ = (mi_) * 16 + idx; const f32x4 t_ = (v_); u32x2 pk_; pk_.x = pk2(t_.x, t_.y); pk_.y = pk2(t_.z, t_.w); \
;         *(u32x2*)(wl + r_ * 128 + ((((ni_) * 2 + (kq >> 1)) ^ (r_ & 7)) * 16) + (kq & 1) * 8) = pk_; } while (0)
; __device__ __forceinline__ float siluf(float v) { return v * __builtin_amdgcn_rcpf(1.f + __builtin_amdgcn_exp2f(-1.4426950408889634f * v)); }
; __device__ void gemm1_phase(const Params& p, int l, int hb, unsigned char* smem) {
;     ...
;             for (int mi = 0; mi < 8; ++mi) {
; #pragma unroll
;                 for (int ni = 0; ni < 4; ++ni) {
;                     f32x4 v = acc[mi][ni];
;                     if (mode == 1) { v.x = siluf(v.x); v.y = siluf(v.y); v.z = siluf(v.z); v.w = siluf(v.w); }
;                     else if (mode == 2) { const f32x4 bb = *(const f32x4*)(bg + ni * 16); v.x = sigmf(v.x + bb.x); v.y = sigmf(v.y + bb.y); v.z = sigmf(v.z + bb.z); v.w = sigmf(v.w + bb.w); }
;                     G1_STG(mi, ni, v);
.Lg1e_silu:
	v_mul_f32_e32 v130, 0xbfb8aa3b, v126
	v_mul_f32_e32 v131, 0xbfb8aa3b, v127
	v_mul_f32_e32 v132, 0xbfb8aa3b, v128
	v_mul_f32_e32 v133, 0xbfb8aa3b, v129
	v_exp_f32_e32 v130, v130
	v_exp_f32_e32 v131, v131
	v_exp_f32_e32 v132, v132
	v_exp_f32_e32 v133, v133
	v_add_f32_e32 v130, 1.0, v130
	v_add_f32_e32 v131, 1.0, v131
	v_add_f32_e32 v132, 1.0, v132
	v_add_f32_e32 v133, 1.0, v133
	v_rcp_f32_e32 v130, v130
	v_rcp_f32_e32 v131, v131
	v_rcp_f32_e32 v132, v132
	v_rcp_f32_e32 v133, v133
	v_pk_mul_f32 v[126:127], v[126:127], v[130:131]
	v_pk_mul_f32 v[128:129], v[128:129], v[132:133]
	v_cvt_pk_bf16_f32 v126, v126, v127
	v_cvt_pk_bf16_f32 v127, v128, v129
	ds_write_b64 v136, v[126:127]
	v_mul_f32_e32 v130, 0xbfb8aa3b, v122
	v_mul_f32_e32 v131, 0xbfb8aa3b, v123
	v_mul_f32_e32 v132, 0xbfb8aa3b, v124
	v_mul_f32_e32 v133, 0xbfb8aa3b, v125
	v_exp_f32_e32 v130, v130
	v_exp_f32_e32 v131, v131
	v_exp_f32_e32 v132, v132
	v_exp_f32_e32 v133, v133
	v_add_f32_e32 v130, 1.0, v130
	v_add_f32_e32 v131, 1.0, v131
	v_add_f32_e32 v132, 1.0, v132
	v_add_f32_e32 v133, 1.0, v133
	v_rcp_f32_e32 v130, v130
	v_rcp_f32_e32 v131, v131
	v_rcp_f32_e32 v132, v132
	v_rcp_f32_e32 v133, v133
	v_pk_mul_f32 v[122:123], v[122:123], v[130:131]
	v_pk_mul_f32 v[124:125], v[124:125], v[132:133]
	v_cvt_pk_bf16_f32 v122, v122, v123
	v_cvt_pk_bf16_f32 v123, v124, v125
	ds_write_b64 v137, v[122:123]
	v_mul_f32_e32 v130, 0xbfb8aa3b, v118
	v_mul_f32_e32 v131, 0xbfb8aa3b, v119
	v_mul_f32_e32 v132, 0xbfb8aa3b, v120
	v_mul_f32_e32 v133, 0xbfb8aa3b, v121
	v_exp_f32_e32 v130, v130
	v_exp_f32_e32 v131, v131
	v_exp_f32_e32 v132, v132
	v_exp_f32_e32 v133, v133
	v_add_f32_e32 v130, 1.0, v130
	v_add_f32_e32 v131, 1.0, v131
	v_add_f32_e32 v132, 1.0, v132
	v_add_f32_e32 v133, 1.0, v133
	v_rcp_f32_e32 v130, v130
	v_rcp_f32_e32 v131, v131
	v_rcp_f32_e32 v132, v132
	v_rcp_f32_e32 v133, v133
	v_pk_mul_f32 v[118:119], v[118:119], v[130:131]
	v_pk_mul_f32 v[120:121], v[120:121], v[132:133]
	v_cvt_pk_bf16_f32 v118, v118, v119
	v_cvt_pk_bf16_f32 v119, v120, v121
	ds_write_b64 v138, v[118:119]
	v_mul_f32_e32 v130, 0xbfb8aa3b, v114
	v_mul_f32_e32 v131, 0xbfb8aa3b, v115
	v_mul_f32_e32 v132, 0xbfb8aa3b, v116
	v_mul_f32_e32 v133, 0xbfb8aa3b, v117
	v_exp_f32_e32 v130, v130
	v_exp_f32_e32 v131, v131
	v_exp_f32_e32 v132, v132
	v_exp_f32_e32 v133, v133
	v_add_f32_e32 v130, 1.0, v130
	v_add_f32_e32 v131, 1.0, v131
	v_add_f32_e32 v132, 1.0, v132
	v_add_f32_e32 v133, 1.0, v133
	v_rcp_f32_e32 v130, v130
	v_rcp_f32_e32 v131, v131
	v_rcp_f32_e32 v132, v132
	v_rcp_f32_e32 v133, v133
	v_pk_mul_f32 v[114:115], v[114:115], v[130:131]
	v_pk_mul_f32 v[116:117], v[116:117], v[132:133]
	v_cvt_pk_bf16_f32 v114, v114, v115
	v_cvt_pk_bf16_f32 v115, v116, v117
	ds_write_b64 v139, v[114:115]
	v_mul_f32_e32 v130, 0xbfb8aa3b, v110
	v_mul_f32_e32 v131, 0xbfb8aa3b, v111
	v_mul_f32_e32 v132, 0xbfb8aa3b, v112
	v_mul_f32_e32 v133, 0xbfb8aa3b, v113
	v_exp_f32_e32 v130, v130
	v_exp_f32_e32 v131, v131
	v_exp_f32_e32 v132, v132
	v_exp_f32_e32 v133, v133
	v_add_f32_e32 v130, 1.0, v130
	v_add_f32_e32 v131, 1.0, v131
	v_add_f32_e32 v132, 1.0, v132
	v_add_f32_e32 v133, 1.0, v133
	v_rcp_f32_e32 v130, v130
	v_rcp_f32_e32 v131, v131
	v_rcp_f32_e32 v132, v132
	v_rcp_f32_e32 v133, v133
	v_pk_mul_f32 v[110:111], v[110:111], v[130:131]
	v_pk_mul_f32 v[112:113], v[112:113], v[132:133]
	v_cvt_pk_bf16_f32 v110, v110, v111
	v_cvt_pk_bf16_f32 v111, v112, v113
	ds_write_b64 v136, v[110:111] offset:2048
	v_mul_f32_e32 v130, 0xbfb8aa3b, v106
	v_mul_f32_e32 v131, 0xbfb8aa3b, v107
	v_mul_f32_e32 v132, 0xbfb8aa3b, v108
	v_mul_f32_e32 v133, 0xbfb8aa3b, v109
	v_exp_f32_e32 v130, v130
	v_exp_f32_e32 v131, v131
	v_exp_f32_e32 v132, v132
	v_exp_f32_e32 v133, v133
	v_add_f32_e32 v130, 1.0, v130
	v_add_f32_e32 v131, 1.0, v131
	v_add_f32_e32 v132, 1.0, v132
	v_add_f32_e32 v133, 1.0, v133
	v_rcp_f32_e32 v130, v130
	v_rcp_f32_e32 v131, v131
	v_rcp_f32_e32 v132, v132
	v_rcp_f32_e32 v133, v133
	v_pk_mul_f32 v[106:107], v[106:107], v[130:131]
	v_pk_mul_f32 v[108:109], v[108:109], v[132:133]
	v_cvt_pk_bf16_f32 v106, v106, v107
	v_cvt_pk_bf16_f32 v107, v108, v109
	ds_write_b64 v137, v[106:107] offset:2048
	v_mul_f32_e32 v130, 0xbfb8aa3b, v102
	v_mul_f32_e32 v131, 0xbfb8aa3b, v103
	v_mul_f32_e32 v132, 0xbfb8aa3b, v104
	v_mul_f32_e32 v133, 0xbfb8aa3b, v105
	v_exp_f32_e32 v130, v130
	v_exp_f32_e32 v131, v131
	v_exp_f32_e32 v132, v132
	v_exp_f32_e32 v133, v133
	v_add_f32_e32 v130, 1.0, v130
	v_add_f32_e32 v131, 1.0, v131
	v_add_f32_e32 v132, 1.0, v132
	v_add_f32_e32 v133, 1.0, v133
	v_rcp_f32_e32 v130, v130
	v_rcp_f32_e32 v131, v131
	v_rcp_f32_e32 v132, v132
	v_rcp_f32_e32 v133, v133
	v_pk_mul_f32 v[102:103], v[102:103], v[130:131]
	v_pk_mul_f32 v[104:105], v[104:105], v[132:133]
	v_cvt_pk_bf16_f32 v102, v102, v103
	v_cvt_pk_bf16_f32 v103, v104, v105
	ds_write_b64 v138, v[102:103] offset:2048
	v_mul_f32_e32 v130, 0xbfb8aa3b, v98
	v_mul_f32_e32 v131, 0xbfb8aa3b, v99
	v_mul_f32_e32 v132, 0xbfb8aa3b, v100
	v_mul_f32_e32 v133, 0xbfb8aa3b, v101
	v_exp_f32_e32 v130, v130
	v_exp_f32_e32 v131, v131
	v_exp_f32_e32 v132, v132
	v_exp_f32_e32 v133, v133
	v_add_f32_e32 v130, 1.0, v130
	v_add_f32_e32 v131, 1.0, v131
	v_add_f32_e32 v132, 1.0, v132
	v_add_f32_e32 v133, 1.0, v133
	v_rcp_f32_e32 v130, v130
	v_rcp_f32_e32 v131, v131
	v_rcp_f32_e32 v132, v132
	v_rcp_f32_e32 v133, v133
	v_pk_mul_f32 v[98:99], v[98:99], v[130:131]
	v_pk_mul_f32 v[100:101], v[100:101], v[132:133]
	v_cvt_pk_bf16_f32 v98, v98, v99
	v_cvt_pk_bf16_f32 v99, v100, v101
	ds_write_b64 v139, v[98:99] offset:2048
	v_mul_f32_e32 v130, 0xbfb8aa3b, v94
	v_mul_f32_e32 v131, 0xbfb8aa3b, v95
	v_mul_f32_e32 v132, 0xbfb8aa3b, v96
; __device__ __forceinline__ float sigmf(float v) { return __builtin_amdgcn_rcpf(1.f + __builtin_amdgcn_exp2f(-1.4426950408889634f * v)); }
; #define G1_STG(mi_, ni_, v_) do { const int r_ = (mi_) * 16 + idx; const f32x4 t_ = (v_); u32x2 pk_; pk_.x = pk2(t_.x, t_.y); pk_.y = pk2(t_.z, t_.w); \
;         *(u32x2*)(wl + r_ * 128 + ((((ni_) * 2 + (kq >> 1)) ^ (r_ & 7)) * 16) + (kq & 1) * 8) = pk_; } while (0)
; __device__ __forceinline__ float siluf(float v) { return v * __builtin_amdgcn_rcpf(1.f + __builtin_amdgcn_exp2f(-1.4426950408889634f * v)); }
; __device__ void gemm1_phase(const Params& p, int l, int hb, unsigned char* smem) {
;     ...
;             for (int mi = 0; mi < 8; ++mi) {
; #pragma unroll
;                 for (int ni = 0; ni < 4; ++ni) {
;                     f32x4 v = acc[mi][ni];
;                     if (mode == 1) { v.x = siluf(v.x); v.y = siluf(v.y); v.z = siluf(v.z); v.w = siluf(v.w); }
;                     else if (mode == 2) { const f32x4 bb = *(const f32x4*)(bg + ni * 16); v.x = sigmf(v.x + bb.x); v.y = sigmf(v.y + bb.y); v.z = sigmf(v.z + bb.z); v.w = sigmf(v.w + bb.w); }
;                     G1_STG(mi, ni, v);
	v_mul_f32_e32 v133, 0xbfb8aa3b, v97
	v_exp_f32_e32 v130, v130
	v_exp_f32_e32 v131, v131
	v_exp_f32_e32 v132, v132
	v_exp_f32_e32 v133, v133
	v_add_f32_e32 v130, 1.0, v130
	v_add_f32_e32 v131, 1.0, v131
	v_add_f32_e32 v132, 1.0, v132
	v_add_f32_e32 v133, 1.0, v133
	v_rcp_f32_e32 v130, v130
	v_rcp_f32_e32 v131, v131
	v_rcp_f32_e32 v132, v132
	v_rcp_f32_e32 v133, v133
	v_pk_mul_f32 v[94:95], v[94:95], v[130:131]
	v_pk_mul_f32 v[96:97], v[96:97], v[132:133]
	v_cvt_pk_bf16_f32 v94, v94, v95
	v_cvt_pk_bf16_f32 v95, v96, v97
	ds_write_b64 v136, v[94:95] offset:4096
	v_mul_f32_e32 v130, 0xbfb8aa3b, v90
	v_mul_f32_e32 v131, 0xbfb8aa3b, v91
	v_mul_f32_e32 v132, 0xbfb8aa3b, v92
	v_mul_f32_e32 v133, 0xbfb8aa3b, v93
	v_exp_f32_e32 v130, v130
	v_exp_f32_e32 v131, v131
	v_exp_f32_e32 v132, v132
	v_exp_f32_e32 v133, v133
	v_add_f32_e32 v130, 1.0, v130
	v_add_f32_e32 v131, 1.0, v131
	v_add_f32_e32 v132, 1.0, v132
	v_add_f32_e32 v133, 1.0, v133
	v_rcp_f32_e32 v130, v130
	v_rcp_f32_e32 v131, v131
	v_rcp_f32_e32 v132, v132
	v_rcp_f32_e32 v133, v133
	v_pk_mul_f32 v[90:91], v[90:91], v[130:131]
	v_pk_mul_f32 v[92:93], v[92:93], v[132:133]
	v_cvt_pk_bf16_f32 v90, v90, v91
	v_cvt_pk_bf16_f32 v91, v92, v93
	ds_write_b64 v137, v[90:91] offset:4096
	v_mul_f32_e32 v130, 0xbfb8aa3b, v86
	v_mul_f32_e32 v131, 0xbfb8aa3b, v87
	v_mul_f32_e32 v132, 0xbfb8aa3b, v88
	v_mul_f32_e32 v133, 0xbfb8aa3b, v89
	v_exp_f32_e32 v130, v130
	v_exp_f32_e32 v131, v131
	v_exp_f32_e32 v132, v132
	v_exp_f32_e32 v133, v133
	v_add_f32_e32 v130, 1.0, v130
	v_add_f32_e32 v131, 1.0, v131
	v_add_f32_e32 v132, 1.0, v132
	v_add_f32_e32 v133, 1.0, v133
	v_rcp_f32_e32 v130, v130
	v_rcp_f32_e32 v131, v131
	v_rcp_f32_e32 v132, v132
	v_rcp_f32_e32 v133, v133
	v_pk_mul_f32 v[86:87], v[86:87], v[130:131]
	v_pk_mul_f32 v[88:89], v[88:89], v[132:133]
	v_cvt_pk_bf16_f32 v86, v86, v87
	v_cvt_pk_bf16_f32 v87, v88, v89
	ds_write_b64 v138, v[86:87] offset:4096
	v_mul_f32_e32 v130, 0xbfb8aa3b, v82
	v_mul_f32_e32 v131, 0xbfb8aa3b, v83
	v_mul_f32_e32 v132, 0xbfb8aa3b, v84
	v_mul_f32_e32 v133, 0xbfb8aa3b, v85
	v_exp_f32_e32 v130, v130
	v_exp_f32_e32 v131, v131
	v_exp_f32_e32 v132, v132
	v_exp_f32_e32 v133, v133
	v_add_f32_e32 v130, 1.0, v130
	v_add_f32_e32 v131, 1.0, v131
	v_add_f32_e32 v132, 1.0, v132
	v_add_f32_e32 v133, 1.0, v133
	v_rcp_f32_e32 v130, v130
	v_rcp_f32_e32 v131, v131
	v_rcp_f32_e32 v132, v132
	v_rcp_f32_e32 v133, v133
	v_pk_mul_f32 v[82:83], v[82:83], v[130:131]
	v_pk_mul_f32 v[84:85], v[84:85], v[132:133]
	v_cvt_pk_bf16_f32 v82, v82, v83
	v_cvt_pk_bf16_f32 v83, v84, v85
	ds_write_b64 v139, v[82:83] offset:4096
	v_mul_f32_e32 v130, 0xbfb8aa3b, v76
	v_mul_f32_e32 v131, 0xbfb8aa3b, v77
	v_mul_f32_e32 v132, 0xbfb8aa3b, v78
	v_mul_f32_e32 v133, 0xbfb8aa3b, v79
	v_exp_f32_e32 v130, v130
	v_exp_f32_e32 v131, v131
	v_exp_f32_e32 v132, v132
	v_exp_f32_e32 v133, v133
	v_add_f32_e32 v130, 1.0, v130
	v_add_f32_e32 v131, 1.0, v131
	v_add_f32_e32 v132, 1.0, v132
	v_add_f32_e32 v133, 1.0, v133
	v_rcp_f32_e32 v130, v130
	v_rcp_f32_e32 v131, v131
	v_rcp_f32_e32 v132, v132
	v_rcp_f32_e32 v133, v133
	v_pk_mul_f32 v[76:77], v[76:77], v[130:131]
	v_pk_mul_f32 v[78:79], v[78:79], v[132:133]
	v_cvt_pk_bf16_f32 v76, v76, v77
	v_cvt_pk_bf16_f32 v77, v78, v79
	ds_write_b64 v136, v[76:77] offset:6144
	v_mul_f32_e32 v130, 0xbfb8aa3b, v72
	v_mul_f32_e32 v131, 0xbfb8aa3b, v73
	v_mul_f32_e32 v132, 0xbfb8aa3b, v74
	v_mul_f32_e32 v133, 0xbfb8aa3b, v75
	v_exp_f32_e32 v130, v130
	v_exp_f32_e32 v131, v131
	v_exp_f32_e32 v132, v132
	v_exp_f32_e32 v133, v133
	v_add_f32_e32 v130, 1.0, v130
	v_add_f32_e32 v131, 1.0, v131
	v_add_f32_e32 v132, 1.0, v132
	v_add_f32_e32 v133, 1.0, v133
	v_rcp_f32_e32 v130, v130
	v_rcp_f32_e32 v131, v131
	v_rcp_f32_e32 v132, v132
	v_rcp_f32_e32 v133, v133
	v_pk_mul_f32 v[72:73], v[72:73], v[130:131]
	v_pk_mul_f32 v[74:75], v[74:75], v[132:133]
	v_cvt_pk_bf16_f32 v72, v72, v73
	v_cvt_pk_bf16_f32 v73, v74, v75
	ds_write_b64 v137, v[72:73] offset:6144
	v_mul_f32_e32 v130, 0xbfb8aa3b, v68
	v_mul_f32_e32 v131, 0xbfb8aa3b, v69
	v_mul_f32_e32 v132, 0xbfb8aa3b, v70
	v_mul_f32_e32 v133, 0xbfb8aa3b, v71
	v_exp_f32_e32 v130, v130
	v_exp_f32_e32 v131, v131
	v_exp_f32_e32 v132, v132
	v_exp_f32_e32 v133, v133
	v_add_f32_e32 v130, 1.0, v130
	v_add_f32_e32 v131, 1.0, v131
	v_add_f32_e32 v132, 1.0, v132
	v_add_f32_e32 v133, 1.0, v133
	v_rcp_f32_e32 v130, v130
	v_rcp_f32_e32 v131, v131
	v_rcp_f32_e32 v132, v132
	v_rcp_f32_e32 v133, v133
	v_pk_mul_f32 v[68:69], v[68:69], v[130:131]
	v_pk_mul_f32 v[70:71], v[70:71], v[132:133]
	v_cvt_pk_bf16_f32 v68, v68, v69
	v_cvt_pk_bf16_f32 v69, v70, v71
	ds_write_b64 v138, v[68:69] offset:6144
	v_mul_f32_e32 v130, 0xbfb8aa3b, v64
	v_mul_f32_e32 v131, 0xbfb8aa3b, v65
	v_mul_f32_e32 v132, 0xbfb8aa3b, v66
	v_mul_f32_e32 v133, 0xbfb8aa3b, v67
	v_exp_f32_e32 v130, v130
	v_exp_f32_e32 v131, v131
	v_exp_f32_e32 v132, v132
	v_exp_f32_e32 v133, v133
	v_add_f32_e32 v130, 1.0, v130
	v_add_f32_e32 v131, 1.0, v131
	v_add_f32_e32 v132, 1.0, v132
	v_add_f32_e32 v133, 1.0, v133
	v_rcp_f32_e32 v130, v130
	v_rcp_f32_e32 v131, v131
	v_rcp_f32_e32 v132, v132
	v_rcp_f32_e32 v133, v133
	v_pk_mul_f32 v[64:65], v[64:65], v[130:131]
	v_pk_mul_f32 v[66:67], v[66:67], v[132:133]
	v_cvt_pk_bf16_f32 v64, v64, v65
	v_cvt_pk_bf16_f32 v65, v66, v67
	ds_write_b64 v139, v[64:65] offset:6144
	v_mul_f32_e32 v130, 0xbfb8aa3b, v60
	v_mul_f32_e32 v131, 0xbfb8aa3b, v61
	v_mul_f32_e32 v132, 0xbfb8aa3b, v62
	v_mul_f32_e32 v133, 0xbfb8aa3b, v63
	v_exp_f32_e32 v130, v130
	v_exp_f32_e32 v131, v131
	v_exp_f32_e32 v132, v132
	v_exp_f32_e32 v133, v133
	v_add_f32_e32 v130, 1.0, v130
	v_add_f32_e32 v131, 1.0, v131
	v_add_f32_e32 v132, 1.0, v132
; __device__ __forceinline__ float sigmf(float v) { return __builtin_amdgcn_rcpf(1.f + __builtin_amdgcn_exp2f(-1.4426950408889634f * v)); }
; #define G1_STG(mi_, ni_, v_) do { const int r_ = (mi_) * 16 + idx; const f32x4 t_ = (v_); u32x2 pk_; pk_.x = pk2(t_.x, t_.y); pk_.y = pk2(t_.z, t_.w); \
;         *(u32x2*)(wl + r_ * 128 + ((((ni_) * 2 + (kq >> 1)) ^ (r_ & 7)) * 16) + (kq & 1) * 8) = pk_; } while (0)
; __device__ __forceinline__ float siluf(float v) { return v * __builtin_amdgcn_rcpf(1.f + __builtin_amdgcn_exp2f(-1.4426950408889634f * v)); }
; __device__ void gemm1_phase(const Params& p, int l, int hb, unsigned char* smem) {
;     ...
;             for (int mi = 0; mi < 8; ++mi) {
; #pragma unroll
;                 for (int ni = 0; ni < 4; ++ni) {
;                     f32x4 v = acc[mi][ni];
;                     if (mode == 1) { v.x = siluf(v.x); v.y = siluf(v.y); v.z = siluf(v.z); v.w = siluf(v.w); }
;                     else if (mode == 2) { const f32x4 bb = *(const f32x4*)(bg + ni * 16); v.x = sigmf(v.x + bb.x); v.y = sigmf(v.y + bb.y); v.z = sigmf(v.z + bb.z); v.w = sigmf(v.w + bb.w); }
;                     G1_STG(mi, ni, v);
	v_add_f32_e32 v133, 1.0, v133
	v_rcp_f32_e32 v130, v130
	v_rcp_f32_e32 v131, v131
	v_rcp_f32_e32 v132, v132
	v_rcp_f32_e32 v133, v133
	v_pk_mul_f32 v[60:61], v[60:61], v[130:131]
	v_pk_mul_f32 v[62:63], v[62:63], v[132:133]
	v_cvt_pk_bf16_f32 v60, v60, v61
	v_cvt_pk_bf16_f32 v61, v62, v63
	ds_write_b64 v136, v[60:61] offset:8192
	v_mul_f32_e32 v130, 0xbfb8aa3b, v56
	v_mul_f32_e32 v131, 0xbfb8aa3b, v57
	v_mul_f32_e32 v132, 0xbfb8aa3b, v58
	v_mul_f32_e32 v133, 0xbfb8aa3b, v59
	v_exp_f32_e32 v130, v130
	v_exp_f32_e32 v131, v131
	v_exp_f32_e32 v132, v132
	v_exp_f32_e32 v133, v133
	v_add_f32_e32 v130, 1.0, v130
	v_add_f32_e32 v131, 1.0, v131
	v_add_f32_e32 v132, 1.0, v132
	v_add_f32_e32 v133, 1.0, v133
	v_rcp_f32_e32 v130, v130
	v_rcp_f32_e32 v131, v131
	v_rcp_f32_e32 v132, v132
	v_rcp_f32_e32 v133, v133
	v_pk_mul_f32 v[56:57], v[56:57], v[130:131]
	v_pk_mul_f32 v[58:59], v[58:59], v[132:133]
	v_cvt_pk_bf16_f32 v56, v56, v57
	v_cvt_pk_bf16_f32 v57, v58, v59
	ds_write_b64 v137, v[56:57] offset:8192
	v_mul_f32_e32 v130, 0xbfb8aa3b, v52
	v_mul_f32_e32 v131, 0xbfb8aa3b, v53
	v_mul_f32_e32 v132, 0xbfb8aa3b, v54
	v_mul_f32_e32 v133, 0xbfb8aa3b, v55
	v_exp_f32_e32 v130, v130
	v_exp_f32_e32 v131, v131
	v_exp_f32_e32 v132, v132
	v_exp_f32_e32 v133, v133
	v_add_f32_e32 v130, 1.0, v130
	v_add_f32_e32 v131, 1.0, v131
	v_add_f32_e32 v132, 1.0, v132
	v_add_f32_e32 v133, 1.0, v133
	v_rcp_f32_e32 v130, v130
	v_rcp_f32_e32 v131, v131
	v_rcp_f32_e32 v132, v132
	v_rcp_f32_e32 v133, v133
	v_pk_mul_f32 v[52:53], v[52:53], v[130:131]
	v_pk_mul_f32 v[54:55], v[54:55], v[132:133]
	v_cvt_pk_bf16_f32 v52, v52, v53
	v_cvt_pk_bf16_f32 v53, v54, v55
	ds_write_b64 v138, v[52:53] offset:8192
	v_mul_f32_e32 v130, 0xbfb8aa3b, v48
	v_mul_f32_e32 v131, 0xbfb8aa3b, v49
	v_mul_f32_e32 v132, 0xbfb8aa3b, v50
	v_mul_f32_e32 v133, 0xbfb8aa3b, v51
	v_exp_f32_e32 v130, v130
	v_exp_f32_e32 v131, v131
	v_exp_f32_e32 v132, v132
	v_exp_f32_e32 v133, v133
	v_add_f32_e32 v130, 1.0, v130
	v_add_f32_e32 v131, 1.0, v131
	v_add_f32_e32 v132, 1.0, v132
	v_add_f32_e32 v133, 1.0, v133
	v_rcp_f32_e32 v130, v130
	v_rcp_f32_e32 v131, v131
	v_rcp_f32_e32 v132, v132
	v_rcp_f32_e32 v133, v133
	v_pk_mul_f32 v[48:49], v[48:49], v[130:131]
	v_pk_mul_f32 v[50:51], v[50:51], v[132:133]
	v_cvt_pk_bf16_f32 v48, v48, v49
	v_cvt_pk_bf16_f32 v49, v50, v51
	ds_write_b64 v139, v[48:49] offset:8192
	v_mul_f32_e32 v130, 0xbfb8aa3b, v44
	v_mul_f32_e32 v131, 0xbfb8aa3b, v45
	v_mul_f32_e32 v132, 0xbfb8aa3b, v46
	v_mul_f32_e32 v133, 0xbfb8aa3b, v47
	v_exp_f32_e32 v130, v130
	v_exp_f32_e32 v131, v131
	v_exp_f32_e32 v132, v132
	v_exp_f32_e32 v133, v133
	v_add_f32_e32 v130, 1.0, v130
	v_add_f32_e32 v131, 1.0, v131
	v_add_f32_e32 v132, 1.0, v132
	v_add_f32_e32 v133, 1.0, v133
	v_rcp_f32_e32 v130, v130
	v_rcp_f32_e32 v131, v131
	v_rcp_f32_e32 v132, v132
	v_rcp_f32_e32 v133, v133
	v_pk_mul_f32 v[44:45], v[44:45], v[130:131]
	v_pk_mul_f32 v[46:47], v[46:47], v[132:133]
	v_cvt_pk_bf16_f32 v44, v44, v45
	v_cvt_pk_bf16_f32 v45, v46, v47
	ds_write_b64 v136, v[44:45] offset:10240
	v_mul_f32_e32 v130, 0xbfb8aa3b, v40
	v_mul_f32_e32 v131, 0xbfb8aa3b, v41
	v_mul_f32_e32 v132, 0xbfb8aa3b, v42
	v_mul_f32_e32 v133, 0xbfb8aa3b, v43
	v_exp_f32_e32 v130, v130
	v_exp_f32_e32 v131, v131
	v_exp_f32_e32 v132, v132
	v_exp_f32_e32 v133, v133
	v_add_f32_e32 v130, 1.0, v130
	v_add_f32_e32 v131, 1.0, v131
	v_add_f32_e32 v132, 1.0, v132
	v_add_f32_e32 v133, 1.0, v133
	v_rcp_f32_e32 v130, v130
	v_rcp_f32_e32 v131, v131
	v_rcp_f32_e32 v132, v132
	v_rcp_f32_e32 v133, v133
	v_pk_mul_f32 v[40:41], v[40:41], v[130:131]
	v_pk_mul_f32 v[42:43], v[42:43], v[132:133]
	v_cvt_pk_bf16_f32 v40, v40, v41
	v_cvt_pk_bf16_f32 v41, v42, v43
	ds_write_b64 v137, v[40:41] offset:10240
	v_mul_f32_e32 v130, 0xbfb8aa3b, v36
	v_mul_f32_e32 v131, 0xbfb8aa3b, v37
	v_mul_f32_e32 v132, 0xbfb8aa3b, v38
	v_mul_f32_e32 v133, 0xbfb8aa3b, v39
	v_exp_f32_e32 v130, v130
	v_exp_f32_e32 v131, v131
	v_exp_f32_e32 v132, v132
	v_exp_f32_e32 v133, v133
	v_add_f32_e32 v130, 1.0, v130
	v_add_f32_e32 v131, 1.0, v131
	v_add_f32_e32 v132, 1.0, v132
	v_add_f32_e32 v133, 1.0, v133
	v_rcp_f32_e32 v130, v130
	v_rcp_f32_e32 v131, v131
	v_rcp_f32_e32 v132, v132
	v_rcp_f32_e32 v133, v133
	v_pk_mul_f32 v[36:37], v[36:37], v[130:131]
	v_pk_mul_f32 v[38:39], v[38:39], v[132:133]
	v_cvt_pk_bf16_f32 v36, v36, v37
	v_cvt_pk_bf16_f32 v37, v38, v39
	ds_write_b64 v138, v[36:37] offset:10240
	v_mul_f32_e32 v130, 0xbfb8aa3b, v32
	v_mul_f32_e32 v131, 0xbfb8aa3b, v33
	v_mul_f32_e32 v132, 0xbfb8aa3b, v34
	v_mul_f32_e32 v133, 0xbfb8aa3b, v35
	v_exp_f32_e32 v130, v130
	v_exp_f32_e32 v131, v131
	v_exp_f32_e32 v132, v132
	v_exp_f32_e32 v133, v133
	v_add_f32_e32 v130, 1.0, v130
	v_add_f32_e32 v131, 1.0, v131
	v_add_f32_e32 v132, 1.0, v132
	v_add_f32_e32 v133, 1.0, v133
	v_rcp_f32_e32 v130, v130
	v_rcp_f32_e32 v131, v131
	v_rcp_f32_e32 v132, v132
	v_rcp_f32_e32 v133, v133
	v_pk_mul_f32 v[32:33], v[32:33], v[130:131]
	v_pk_mul_f32 v[34:35], v[34:35], v[132:133]
	v_cvt_pk_bf16_f32 v32, v32, v33
	v_cvt_pk_bf16_f32 v33, v34, v35
	ds_write_b64 v139, v[32:33] offset:10240
	v_mul_f32_e32 v130, 0xbfb8aa3b, v28
	v_mul_f32_e32 v131, 0xbfb8aa3b, v29
	v_mul_f32_e32 v132, 0xbfb8aa3b, v30
	v_mul_f32_e32 v133, 0xbfb8aa3b, v31
	v_exp_f32_e32 v130, v130
	v_exp_f32_e32 v131, v131
	v_exp_f32_e32 v132, v132
	v_exp_f32_e32 v133, v133
	v_add_f32_e32 v130, 1.0, v130
	v_add_f32_e32 v131, 1.0, v131
	v_add_f32_e32 v132, 1.0, v132
	v_add_f32_e32 v133, 1.0, v133
	v_rcp_f32_e32 v130, v130
	v_rcp_f32_e32 v131, v131
	v_rcp_f32_e32 v132, v132
	v_rcp_f32_e32 v133, v133
	v_pk_mul_f32 v[28:29], v[28:29], v[130:131]
	v_pk_mul_f32 v[30:31], v[30:31], v[132:133]
; __device__ __forceinline__ float siluf(float v) { return v * __builtin_amdgcn_rcpf(1.f + __builtin_amdgcn_exp2f(-1.4426950408889634f * v)); }
; __device__ __forceinline__ float sigmf(float v) { return __builtin_amdgcn_rcpf(1.f + __builtin_amdgcn_exp2f(-1.4426950408889634f * v)); }
; #define G1_STG(mi_, ni_, v_) do { const int r_ = (mi_) * 16 + idx; const f32x4 t_ = (v_); u32x2 pk_; pk_.x = pk2(t_.x, t_.y); pk_.y = pk2(t_.z, t_.w); \
;         *(u32x2*)(wl + r_ * 128 + ((((ni_) * 2 + (kq >> 1)) ^ (r_ & 7)) * 16) + (kq & 1) * 8) = pk_; } while (0)
; __device__ void gemm1_phase(const Params& p, int l, int hb, unsigned char* smem) {
;     ...
; #pragma unroll
;             for (int mi = 0; mi < 8; ++mi) {
; #pragma unroll
;                 for (int ni = 0; ni < 4; ++ni) {
;                     f32x4 v = acc[mi][ni];
;                     if (mode == 1) { v.x = siluf(v.x); v.y = siluf(v.y); v.z = siluf(v.z); v.w = siluf(v.w); }
;                     else if (mode == 2) { const f32x4 bb = *(const f32x4*)(bg + ni * 16); v.x = sigmf(v.x + bb.x); v.y = sigmf(v.y + bb.y); v.z = sigmf(v.z + bb.z); v.w = sigmf(v.w + bb.w); }
;                     G1_STG(mi, ni, v);
;                 }
	v_cvt_pk_bf16_f32 v28, v28, v29
	v_cvt_pk_bf16_f32 v29, v30, v31
	ds_write_b64 v136, v[28:29] offset:12288
	v_mul_f32_e32 v130, 0xbfb8aa3b, v24
	v_mul_f32_e32 v131, 0xbfb8aa3b, v25
	v_mul_f32_e32 v132, 0xbfb8aa3b, v26
	v_mul_f32_e32 v133, 0xbfb8aa3b, v27
	v_exp_f32_e32 v130, v130
	v_exp_f32_e32 v131, v131
	v_exp_f32_e32 v132, v132
	v_exp_f32_e32 v133, v133
	v_add_f32_e32 v130, 1.0, v130
	v_add_f32_e32 v131, 1.0, v131
	v_add_f32_e32 v132, 1.0, v132
	v_add_f32_e32 v133, 1.0, v133
	v_rcp_f32_e32 v130, v130
	v_rcp_f32_e32 v131, v131
	v_rcp_f32_e32 v132, v132
	v_rcp_f32_e32 v133, v133
	v_pk_mul_f32 v[24:25], v[24:25], v[130:131]
	v_pk_mul_f32 v[26:27], v[26:27], v[132:133]
	v_cvt_pk_bf16_f32 v24, v24, v25
	v_cvt_pk_bf16_f32 v25, v26, v27
	ds_write_b64 v137, v[24:25] offset:12288
	v_mul_f32_e32 v130, 0xbfb8aa3b, v20
	v_mul_f32_e32 v131, 0xbfb8aa3b, v21
	v_mul_f32_e32 v132, 0xbfb8aa3b, v22
	v_mul_f32_e32 v133, 0xbfb8aa3b, v23
	v_exp_f32_e32 v130, v130
	v_exp_f32_e32 v131, v131
	v_exp_f32_e32 v132, v132
	v_exp_f32_e32 v133, v133
	v_add_f32_e32 v130, 1.0, v130
	v_add_f32_e32 v131, 1.0, v131
	v_add_f32_e32 v132, 1.0, v132
	v_add_f32_e32 v133, 1.0, v133
	v_rcp_f32_e32 v130, v130
	v_rcp_f32_e32 v131, v131
	v_rcp_f32_e32 v132, v132
	v_rcp_f32_e32 v133, v133
	v_pk_mul_f32 v[20:21], v[20:21], v[130:131]
	v_pk_mul_f32 v[22:23], v[22:23], v[132:133]
	v_cvt_pk_bf16_f32 v20, v20, v21
	v_cvt_pk_bf16_f32 v21, v22, v23
	ds_write_b64 v138, v[20:21] offset:12288
	v_mul_f32_e32 v130, 0xbfb8aa3b, v16
	v_mul_f32_e32 v131, 0xbfb8aa3b, v17
	v_mul_f32_e32 v132, 0xbfb8aa3b, v18
	v_mul_f32_e32 v133, 0xbfb8aa3b, v19
	v_exp_f32_e32 v130, v130
	v_exp_f32_e32 v131, v131
	v_exp_f32_e32 v132, v132
	v_exp_f32_e32 v133, v133
	v_add_f32_e32 v130, 1.0, v130
	v_add_f32_e32 v131, 1.0, v131
	v_add_f32_e32 v132, 1.0, v132
	v_add_f32_e32 v133, 1.0, v133
	v_rcp_f32_e32 v130, v130
	v_rcp_f32_e32 v131, v131
	v_rcp_f32_e32 v132, v132
	v_rcp_f32_e32 v133, v133
	v_pk_mul_f32 v[16:17], v[16:17], v[130:131]
	v_pk_mul_f32 v[18:19], v[18:19], v[132:133]
	v_cvt_pk_bf16_f32 v16, v16, v17
	v_cvt_pk_bf16_f32 v17, v18, v19
	ds_write_b64 v139, v[16:17] offset:12288
	v_mul_f32_e32 v130, 0xbfb8aa3b, v12
	v_mul_f32_e32 v131, 0xbfb8aa3b, v13
	v_mul_f32_e32 v132, 0xbfb8aa3b, v14
	v_mul_f32_e32 v133, 0xbfb8aa3b, v15
	v_exp_f32_e32 v130, v130
	v_exp_f32_e32 v131, v131
	v_exp_f32_e32 v132, v132
	v_exp_f32_e32 v133, v133
	v_add_f32_e32 v130, 1.0, v130
	v_add_f32_e32 v131, 1.0, v131
	v_add_f32_e32 v132, 1.0, v132
	v_add_f32_e32 v133, 1.0, v133
	v_rcp_f32_e32 v130, v130
	v_rcp_f32_e32 v131, v131
	v_rcp_f32_e32 v132, v132
	v_rcp_f32_e32 v133, v133
	v_pk_mul_f32 v[12:13], v[12:13], v[130:131]
	v_pk_mul_f32 v[14:15], v[14:15], v[132:133]
	v_cvt_pk_bf16_f32 v12, v12, v13
	v_cvt_pk_bf16_f32 v13, v14, v15
	ds_write_b64 v136, v[12:13] offset:14336
	v_mul_f32_e32 v130, 0xbfb8aa3b, v8
	v_mul_f32_e32 v131, 0xbfb8aa3b, v9
	v_mul_f32_e32 v132, 0xbfb8aa3b, v10
	v_mul_f32_e32 v133, 0xbfb8aa3b, v11
	v_exp_f32_e32 v130, v130
	v_exp_f32_e32 v131, v131
	v_exp_f32_e32 v132, v132
	v_exp_f32_e32 v133, v133
	v_add_f32_e32 v130, 1.0, v130
	v_add_f32_e32 v131, 1.0, v131
	v_add_f32_e32 v132, 1.0, v132
	v_add_f32_e32 v133, 1.0, v133
	v_rcp_f32_e32 v130, v130
	v_rcp_f32_e32 v131, v131
	v_rcp_f32_e32 v132, v132
	v_rcp_f32_e32 v133, v133
	v_pk_mul_f32 v[8:9], v[8:9], v[130:131]
	v_pk_mul_f32 v[10:11], v[10:11], v[132:133]
	v_cvt_pk_bf16_f32 v8, v8, v9
	v_cvt_pk_bf16_f32 v9, v10, v11
	ds_write_b64 v137, v[8:9] offset:14336
	v_mul_f32_e32 v130, 0xbfb8aa3b, v4
	v_mul_f32_e32 v131, 0xbfb8aa3b, v5
	v_mul_f32_e32 v132, 0xbfb8aa3b, v6
	v_mul_f32_e32 v133, 0xbfb8aa3b, v7
	v_exp_f32_e32 v130, v130
	v_exp_f32_e32 v131, v131
	v_exp_f32_e32 v132, v132
	v_exp_f32_e32 v133, v133
	v_add_f32_e32 v130, 1.0, v130
	v_add_f32_e32 v131, 1.0, v131
	v_add_f32_e32 v132, 1.0, v132
	v_add_f32_e32 v133, 1.0, v133
	v_rcp_f32_e32 v130, v130
	v_rcp_f32_e32 v131, v131
	v_rcp_f32_e32 v132, v132
	v_rcp_f32_e32 v133, v133
	v_pk_mul_f32 v[4:5], v[4:5], v[130:131]
	v_pk_mul_f32 v[6:7], v[6:7], v[132:133]
	v_cvt_pk_bf16_f32 v4, v4, v5
	v_cvt_pk_bf16_f32 v5, v6, v7
	ds_write_b64 v138, v[4:5] offset:14336
	v_mul_f32_e32 v130, 0xbfb8aa3b, v0
	v_mul_f32_e32 v131, 0xbfb8aa3b, v1
	v_mul_f32_e32 v132, 0xbfb8aa3b, v2
	v_mul_f32_e32 v133, 0xbfb8aa3b, v3
	v_exp_f32_e32 v130, v130
	v_exp_f32_e32 v131, v131
	v_exp_f32_e32 v132, v132
	v_exp_f32_e32 v133, v133
	v_add_f32_e32 v130, 1.0, v130
	v_add_f32_e32 v131, 1.0, v131
	v_add_f32_e32 v132, 1.0, v132
	v_add_f32_e32 v133, 1.0, v133
	v_rcp_f32_e32 v130, v130
	v_rcp_f32_e32 v131, v131
	v_rcp_f32_e32 v132, v132
	v_rcp_f32_e32 v133, v133
	v_pk_mul_f32 v[0:1], v[0:1], v[130:131]
	v_pk_mul_f32 v[2:3], v[2:3], v[132:133]
	v_cvt_pk_bf16_f32 v0, v0, v1
	v_cvt_pk_bf16_f32 v1, v2, v3
	ds_write_b64 v139, v[0:1] offset:14336
	s_branch .Lg1e_done
; __device__ __forceinline__ float siluf(float v) { return v * __builtin_amdgcn_rcpf(1.f + __builtin_amdgcn_exp2f(-1.4426950408889634f * v)); }
; __device__ __forceinline__ float sigmf(float v) { return __builtin_amdgcn_rcpf(1.f + __builtin_amdgcn_exp2f(-1.4426950408889634f * v)); }
; #define G1_STG(mi_, ni_, v_) do { const int r_ = (mi_) * 16 + idx; const f32x4 t_ = (v_); u32x2 pk_; pk_.x = pk2(t_.x, t_.y); pk_.y = pk2(t_.z, t_.w); \
;         *(u32x2*)(wl + r_ * 128 + ((((ni_) * 2 + (kq >> 1)) ^ (r_ & 7)) * 16) + (kq & 1) * 8) = pk_; } while (0)
; __device__ void gemm1_phase(const Params& p, int l, int hb, unsigned char* smem) {
;     ...
;             const float* bg = p.b_gate + l * 3072 + dc0 + lc;
; #pragma unroll
;             for (int mi = 0; mi < 8; ++mi) {
; #pragma unroll
;                 for (int ni = 0; ni < 4; ++ni) {
;                     f32x4 v = acc[mi][ni];
;                     if (mode == 1) { v.x = siluf(v.x); v.y = siluf(v.y); v.z = siluf(v.z); v.w = siluf(v.w); }
;                     else if (mode == 2) { const f32x4 bb = *(const f32x4*)(bg + ni * 16); v.x = sigmf(v.x + bb.x); v.y = sigmf(v.y + bb.y); v.z = sigmf(v.z + bb.z); v.w = sigmf(v.w + bb.w); }
;                     G1_STG(mi, ni, v);
;                 }
.Lg1e_sig:
	s_waitcnt vmcnt(0)
	v_add_f32_e32 v130, v126, v160
	v_add_f32_e32 v131, v127, v161
	v_add_f32_e32 v132, v128, v162
	v_add_f32_e32 v133, v129, v163
	v_mul_f32_e32 v130, 0xbfb8aa3b, v130
	v_mul_f32_e32 v131, 0xbfb8aa3b, v131
	v_mul_f32_e32 v132, 0xbfb8aa3b, v132
	v_mul_f32_e32 v133, 0xbfb8aa3b, v133
	v_exp_f32_e32 v130, v130
	v_exp_f32_e32 v131, v131
	v_exp_f32_e32 v132, v132
	v_exp_f32_e32 v133, v133
	v_add_f32_e32 v130, 1.0, v130
	v_add_f32_e32 v131, 1.0, v131
	v_add_f32_e32 v132, 1.0, v132
	v_add_f32_e32 v133, 1.0, v133
	v_rcp_f32_e32 v130, v130
	v_rcp_f32_e32 v131, v131
	v_rcp_f32_e32 v132, v132
	v_rcp_f32_e32 v133, v133
	s_nop 0
	v_cvt_pk_bf16_f32 v126, v130, v131
	v_cvt_pk_bf16_f32 v127, v132, v133
	ds_write_b64 v136, v[126:127]
	v_add_f32_e32 v130, v122, v164
	v_add_f32_e32 v131, v123, v165
	v_add_f32_e32 v132, v124, v166
	v_add_f32_e32 v133, v125, v167
	v_mul_f32_e32 v130, 0xbfb8aa3b, v130
	v_mul_f32_e32 v131, 0xbfb8aa3b, v131
	v_mul_f32_e32 v132, 0xbfb8aa3b, v132
	v_mul_f32_e32 v133, 0xbfb8aa3b, v133
	v_exp_f32_e32 v130, v130
	v_exp_f32_e32 v131, v131
	v_exp_f32_e32 v132, v132
	v_exp_f32_e32 v133, v133
	v_add_f32_e32 v130, 1.0, v130
	v_add_f32_e32 v131, 1.0, v131
	v_add_f32_e32 v132, 1.0, v132
	v_add_f32_e32 v133, 1.0, v133
	v_rcp_f32_e32 v130, v130
	v_rcp_f32_e32 v131, v131
	v_rcp_f32_e32 v132, v132
	v_rcp_f32_e32 v133, v133
	s_nop 0
	v_cvt_pk_bf16_f32 v122, v130, v131
	v_cvt_pk_bf16_f32 v123, v132, v133
	ds_write_b64 v137, v[122:123]
	v_add_f32_e32 v130, v118, v168
	v_add_f32_e32 v131, v119, v169
	v_add_f32_e32 v132, v120, v170
	v_add_f32_e32 v133, v121, v171
	v_mul_f32_e32 v130, 0xbfb8aa3b, v130
	v_mul_f32_e32 v131, 0xbfb8aa3b, v131
	v_mul_f32_e32 v132, 0xbfb8aa3b, v132
	v_mul_f32_e32 v133, 0xbfb8aa3b, v133
	v_exp_f32_e32 v130, v130
	v_exp_f32_e32 v131, v131
	v_exp_f32_e32 v132, v132
	v_exp_f32_e32 v133, v133
	v_add_f32_e32 v130, 1.0, v130
	v_add_f32_e32 v131, 1.0, v131
	v_add_f32_e32 v132, 1.0, v132
	v_add_f32_e32 v133, 1.0, v133
	v_rcp_f32_e32 v130, v130
	v_rcp_f32_e32 v131, v131
	v_rcp_f32_e32 v132, v132
	v_rcp_f32_e32 v133, v133
	s_nop 0
	v_cvt_pk_bf16_f32 v118, v130, v131
	v_cvt_pk_bf16_f32 v119, v132, v133
	ds_write_b64 v138, v[118:119]
	v_add_f32_e32 v130, v114, v172
	v_add_f32_e32 v131, v115, v173
	v_add_f32_e32 v132, v116, v174
	v_add_f32_e32 v133, v117, v175
	v_mul_f32_e32 v130, 0xbfb8aa3b, v130
	v_mul_f32_e32 v131, 0xbfb8aa3b, v131
	v_mul_f32_e32 v132, 0xbfb8aa3b, v132
	v_mul_f32_e32 v133, 0xbfb8aa3b, v133
	v_exp_f32_e32 v130, v130
	v_exp_f32_e32 v131, v131
	v_exp_f32_e32 v132, v132
	v_exp_f32_e32 v133, v133
	v_add_f32_e32 v130, 1.0, v130
	v_add_f32_e32 v131, 1.0, v131
	v_add_f32_e32 v132, 1.0, v132
	v_add_f32_e32 v133, 1.0, v133
	v_rcp_f32_e32 v130, v130
	v_rcp_f32_e32 v131, v131
	v_rcp_f32_e32 v132, v132
	v_rcp_f32_e32 v133, v133
	s_nop 0
	v_cvt_pk_bf16_f32 v114, v130, v131
	v_cvt_pk_bf16_f32 v115, v132, v133
	ds_write_b64 v139, v[114:115]
	v_add_f32_e32 v130, v110, v160
	v_add_f32_e32 v131, v111, v161
	v_add_f32_e32 v132, v112, v162
	v_add_f32_e32 v133, v113, v163
	v_mul_f32_e32 v130, 0xbfb8aa3b, v130
	v_mul_f32_e32 v131, 0xbfb8aa3b, v131
	v_mul_f32_e32 v132, 0xbfb8aa3b, v132
	v_mul_f32_e32 v133, 0xbfb8aa3b, v133
	v_exp_f32_e32 v130, v130
	v_exp_f32_e32 v131, v131
	v_exp_f32_e32 v132, v132
	v_exp_f32_e32 v133, v133
	v_add_f32_e32 v130, 1.0, v130
	v_add_f32_e32 v131, 1.0, v131
	v_add_f32_e32 v132, 1.0, v132
	v_add_f32_e32 v133, 1.0, v133
	v_rcp_f32_e32 v130, v130
	v_rcp_f32_e32 v131, v131
	v_rcp_f32_e32 v132, v132
	v_rcp_f32_e32 v133, v133
	s_nop 0
	v_cvt_pk_bf16_f32 v110, v130, v131
	v_cvt_pk_bf16_f32 v111, v132, v133
	ds_write_b64 v136, v[110:111] offset:2048
	v_add_f32_e32 v130, v106, v164
	v_add_f32_e32 v131, v107, v165
	v_add_f32_e32 v132, v108, v166
	v_add_f32_e32 v133, v109, v167
	v_mul_f32_e32 v130, 0xbfb8aa3b, v130
	v_mul_f32_e32 v131, 0xbfb8aa3b, v131
	v_mul_f32_e32 v132, 0xbfb8aa3b, v132
	v_mul_f32_e32 v133, 0xbfb8aa3b, v133
	v_exp_f32_e32 v130, v130
	v_exp_f32_e32 v131, v131
	v_exp_f32_e32 v132, v132
	v_exp_f32_e32 v133, v133
	v_add_f32_e32 v130, 1.0, v130
	v_add_f32_e32 v131, 1.0, v131
	v_add_f32_e32 v132, 1.0, v132
	v_add_f32_e32 v133, 1.0, v133
	v_rcp_f32_e32 v130, v130
	v_rcp_f32_e32 v131, v131
	v_rcp_f32_e32 v132, v132
	v_rcp_f32_e32 v133, v133
	s_nop 0
	v_cvt_pk_bf16_f32 v106, v130, v131
	v_cvt_pk_bf16_f32 v107, v132, v133
	ds_write_b64 v137, v[106:107] offset:2048
	v_add_f32_e32 v130, v102, v168
	v_add_f32_e32 v131, v103, v169
	v_add_f32_e32 v132, v104, v170
	v_add_f32_e32 v133, v105, v171
	v_mul_f32_e32 v130, 0xbfb8aa3b, v130
	v_mul_f32_e32 v131, 0xbfb8aa3b, v131
	v_mul_f32_e32 v132, 0xbfb8aa3b, v132
	v_mul_f32_e32 v133, 0xbfb8aa3b, v133
	v_exp_f32_e32 v130, v130
	v_exp_f32_e32 v131, v131
	v_exp_f32_e32 v132, v132
	v_exp_f32_e32 v133, v133
	v_add_f32_e32 v130, 1.0, v130
	v_add_f32_e32 v131, 1.0, v131
	v_add_f32_e32 v132, 1.0, v132
	v_add_f32_e32 v133, 1.0, v133
	v_rcp_f32_e32 v130, v130
	v_rcp_f32_e32 v131, v131
	v_rcp_f32_e32 v132, v132
	v_rcp_f32_e32 v133, v133
	s_nop 0
	v_cvt_pk_bf16_f32 v102, v130, v131
	v_cvt_pk_bf16_f32 v103, v132, v133
	ds_write_b64 v138, v[102:103] offset:2048
	v_add_f32_e32 v130, v98, v172
	v_add_f32_e32 v131, v99, v173
	v_add_f32_e32 v132, v100, v174
	v_add_f32_e32 v133, v101, v175
	v_mul_f32_e32 v130, 0xbfb8aa3b, v130
	v_mul_f32_e32 v131, 0xbfb8aa3b, v131
	v_mul_f32_e32 v132, 0xbfb8aa3b, v132
	v_mul_f32_e32 v133, 0xbfb8aa3b, v133
	v_exp_f32_e32 v130, v130
	v_exp_f32_e32 v131, v131
	v_exp_f32_e32 v132, v132
	v_exp_f32_e32 v133, v133
	v_add_f32_e32 v130, 1.0, v130
	v_add_f32_e32 v131, 1.0, v131
	v_add_f32_e32 v132, 1.0, v132
	v_add_f32_e32 v133, 1.0, v133
; __device__ __forceinline__ float siluf(float v) { return v * __builtin_amdgcn_rcpf(1.f + __builtin_amdgcn_exp2f(-1.4426950408889634f * v)); }
; __device__ __forceinline__ float sigmf(float v) { return __builtin_amdgcn_rcpf(1.f + __builtin_amdgcn_exp2f(-1.4426950408889634f * v)); }
; #define G1_STG(mi_, ni_, v_) do { const int r_ = (mi_) * 16 + idx; const f32x4 t_ = (v_); u32x2 pk_; pk_.x = pk2(t_.x, t_.y); pk_.y = pk2(t_.z, t_.w); \
;         *(u32x2*)(wl + r_ * 128 + ((((ni_) * 2 + (kq >> 1)) ^ (r_ & 7)) * 16) + (kq & 1) * 8) = pk_; } while (0)
; __device__ void gemm1_phase(const Params& p, int l, int hb, unsigned char* smem) {
;     ...
;             const float* bg = p.b_gate + l * 3072 + dc0 + lc;
; #pragma unroll
;             for (int mi = 0; mi < 8; ++mi) {
; #pragma unroll
;                 for (int ni = 0; ni < 4; ++ni) {
;                     f32x4 v = acc[mi][ni];
;                     if (mode == 1) { v.x = siluf(v.x); v.y = siluf(v.y); v.z = siluf(v.z); v.w = siluf(v.w); }
;                     else if (mode == 2) { const f32x4 bb = *(const f32x4*)(bg + ni * 16); v.x = sigmf(v.x + bb.x); v.y = sigmf(v.y + bb.y); v.z = sigmf(v.z + bb.z); v.w = sigmf(v.w + bb.w); }
;                     G1_STG(mi, ni, v);
;                 }
	v_rcp_f32_e32 v130, v130
	v_rcp_f32_e32 v131, v131
	v_rcp_f32_e32 v132, v132
	v_rcp_f32_e32 v133, v133
	s_nop 0
	v_cvt_pk_bf16_f32 v98, v130, v131
	v_cvt_pk_bf16_f32 v99, v132, v133
	ds_write_b64 v139, v[98:99] offset:2048
	v_add_f32_e32 v130, v94, v160
	v_add_f32_e32 v131, v95, v161
	v_add_f32_e32 v132, v96, v162
	v_add_f32_e32 v133, v97, v163
	v_mul_f32_e32 v130, 0xbfb8aa3b, v130
	v_mul_f32_e32 v131, 0xbfb8aa3b, v131
	v_mul_f32_e32 v132, 0xbfb8aa3b, v132
	v_mul_f32_e32 v133, 0xbfb8aa3b, v133
	v_exp_f32_e32 v130, v130
	v_exp_f32_e32 v131, v131
	v_exp_f32_e32 v132, v132
	v_exp_f32_e32 v133, v133
	v_add_f32_e32 v130, 1.0, v130
	v_add_f32_e32 v131, 1.0, v131
	v_add_f32_e32 v132, 1.0, v132
	v_add_f32_e32 v133, 1.0, v133
	v_rcp_f32_e32 v130, v130
	v_rcp_f32_e32 v131, v131
	v_rcp_f32_e32 v132, v132
	v_rcp_f32_e32 v133, v133
	s_nop 0
	v_cvt_pk_bf16_f32 v94, v130, v131
	v_cvt_pk_bf16_f32 v95, v132, v133
	ds_write_b64 v136, v[94:95] offset:4096
	v_add_f32_e32 v130, v90, v164
	v_add_f32_e32 v131, v91, v165
	v_add_f32_e32 v132, v92, v166
	v_add_f32_e32 v133, v93, v167
	v_mul_f32_e32 v130, 0xbfb8aa3b, v130
	v_mul_f32_e32 v131, 0xbfb8aa3b, v131
	v_mul_f32_e32 v132, 0xbfb8aa3b, v132
	v_mul_f32_e32 v133, 0xbfb8aa3b, v133
	v_exp_f32_e32 v130, v130
	v_exp_f32_e32 v131, v131
	v_exp_f32_e32 v132, v132
	v_exp_f32_e32 v133, v133
	v_add_f32_e32 v130, 1.0, v130
	v_add_f32_e32 v131, 1.0, v131
	v_add_f32_e32 v132, 1.0, v132
	v_add_f32_e32 v133, 1.0, v133
	v_rcp_f32_e32 v130, v130
	v_rcp_f32_e32 v131, v131
	v_rcp_f32_e32 v132, v132
	v_rcp_f32_e32 v133, v133
	s_nop 0
	v_cvt_pk_bf16_f32 v90, v130, v131
	v_cvt_pk_bf16_f32 v91, v132, v133
	ds_write_b64 v137, v[90:91] offset:4096
	v_add_f32_e32 v130, v86, v168
	v_add_f32_e32 v131, v87, v169
	v_add_f32_e32 v132, v88, v170
	v_add_f32_e32 v133, v89, v171
	v_mul_f32_e32 v130, 0xbfb8aa3b, v130
	v_mul_f32_e32 v131, 0xbfb8aa3b, v131
	v_mul_f32_e32 v132, 0xbfb8aa3b, v132
	v_mul_f32_e32 v133, 0xbfb8aa3b, v133
	v_exp_f32_e32 v130, v130
	v_exp_f32_e32 v131, v131
	v_exp_f32_e32 v132, v132
	v_exp_f32_e32 v133, v133
	v_add_f32_e32 v130, 1.0, v130
	v_add_f32_e32 v131, 1.0, v131
	v_add_f32_e32 v132, 1.0, v132
	v_add_f32_e32 v133, 1.0, v133
	v_rcp_f32_e32 v130, v130
	v_rcp_f32_e32 v131, v131
	v_rcp_f32_e32 v132, v132
	v_rcp_f32_e32 v133, v133
	s_nop 0
	v_cvt_pk_bf16_f32 v86, v130, v131
	v_cvt_pk_bf16_f32 v87, v132, v133
	ds_write_b64 v138, v[86:87] offset:4096
	v_add_f32_e32 v130, v82, v172
	v_add_f32_e32 v131, v83, v173
	v_add_f32_e32 v132, v84, v174
	v_add_f32_e32 v133, v85, v175
	v_mul_f32_e32 v130, 0xbfb8aa3b, v130
	v_mul_f32_e32 v131, 0xbfb8aa3b, v131
	v_mul_f32_e32 v132, 0xbfb8aa3b, v132
	v_mul_f32_e32 v133, 0xbfb8aa3b, v133
	v_exp_f32_e32 v130, v130
	v_exp_f32_e32 v131, v131
	v_exp_f32_e32 v132, v132
	v_exp_f32_e32 v133, v133
	v_add_f32_e32 v130, 1.0, v130
	v_add_f32_e32 v131, 1.0, v131
	v_add_f32_e32 v132, 1.0, v132
	v_add_f32_e32 v133, 1.0, v133
	v_rcp_f32_e32 v130, v130
	v_rcp_f32_e32 v131, v131
	v_rcp_f32_e32 v132, v132
	v_rcp_f32_e32 v133, v133
	s_nop 0
	v_cvt_pk_bf16_f32 v82, v130, v131
	v_cvt_pk_bf16_f32 v83, v132, v133
	ds_write_b64 v139, v[82:83] offset:4096
	v_add_f32_e32 v130, v76, v160
	v_add_f32_e32 v131, v77, v161
	v_add_f32_e32 v132, v78, v162
	v_add_f32_e32 v133, v79, v163
	v_mul_f32_e32 v130, 0xbfb8aa3b, v130
	v_mul_f32_e32 v131, 0xbfb8aa3b, v131
	v_mul_f32_e32 v132, 0xbfb8aa3b, v132
	v_mul_f32_e32 v133, 0xbfb8aa3b, v133
	v_exp_f32_e32 v130, v130
	v_exp_f32_e32 v131, v131
	v_exp_f32_e32 v132, v132
	v_exp_f32_e32 v133, v133
	v_add_f32_e32 v130, 1.0, v130
	v_add_f32_e32 v131, 1.0, v131
	v_add_f32_e32 v132, 1.0, v132
	v_add_f32_e32 v133, 1.0, v133
	v_rcp_f32_e32 v130, v130
	v_rcp_f32_e32 v131, v131
	v_rcp_f32_e32 v132, v132
	v_rcp_f32_e32 v133, v133
	s_nop 0
	v_cvt_pk_bf16_f32 v76, v130, v131
	v_cvt_pk_bf16_f32 v77, v132, v133
	ds_write_b64 v136, v[76:77] offset:6144
	v_add_f32_e32 v130, v72, v164
	v_add_f32_e32 v131, v73, v165
	v_add_f32_e32 v132, v74, v166
	v_add_f32_e32 v133, v75, v167
	v_mul_f32_e32 v130, 0xbfb8aa3b, v130
	v_mul_f32_e32 v131, 0xbfb8aa3b, v131
	v_mul_f32_e32 v132, 0xbfb8aa3b, v132
	v_mul_f32_e32 v133, 0xbfb8aa3b, v133
	v_exp_f32_e32 v130, v130
	v_exp_f32_e32 v131, v131
	v_exp_f32_e32 v132, v132
	v_exp_f32_e32 v133, v133
	v_add_f32_e32 v130, 1.0, v130
	v_add_f32_e32 v131, 1.0, v131
	v_add_f32_e32 v132, 1.0, v132
	v_add_f32_e32 v133, 1.0, v133
	v_rcp_f32_e32 v130, v130
	v_rcp_f32_e32 v131, v131
	v_rcp_f32_e32 v132, v132
	v_rcp_f32_e32 v133, v133
	s_nop 0
	v_cvt_pk_bf16_f32 v72, v130, v131
	v_cvt_pk_bf16_f32 v73, v132, v133
	ds_write_b64 v137, v[72:73] offset:6144
	v_add_f32_e32 v130, v68, v168
	v_add_f32_e32 v131, v69, v169
	v_add_f32_e32 v132, v70, v170
	v_add_f32_e32 v133, v71, v171
	v_mul_f32_e32 v130, 0xbfb8aa3b, v130
	v_mul_f32_e32 v131, 0xbfb8aa3b, v131
	v_mul_f32_e32 v132, 0xbfb8aa3b, v132
	v_mul_f32_e32 v133, 0xbfb8aa3b, v133
	v_exp_f32_e32 v130, v130
	v_exp_f32_e32 v131, v131
	v_exp_f32_e32 v132, v132
	v_exp_f32_e32 v133, v133
	v_add_f32_e32 v130, 1.0, v130
	v_add_f32_e32 v131, 1.0, v131
	v_add_f32_e32 v132, 1.0, v132
	v_add_f32_e32 v133, 1.0, v133
	v_rcp_f32_e32 v130, v130
	v_rcp_f32_e32 v131, v131
	v_rcp_f32_e32 v132, v132
	v_rcp_f32_e32 v133, v133
	s_nop 0
	v_cvt_pk_bf16_f32 v68, v130, v131
	v_cvt_pk_bf16_f32 v69, v132, v133
	ds_write_b64 v138, v[68:69] offset:6144
	v_add_f32_e32 v130, v64, v172
	v_add_f32_e32 v131, v65, v173
	v_add_f32_e32 v132, v66, v174
	v_add_f32_e32 v133, v67, v175
	v_mul_f32_e32 v130, 0xbfb8aa3b, v130
	v_mul_f32_e32 v131, 0xbfb8aa3b, v131
	v_mul_f32_e32 v132, 0xbfb8aa3b, v132
	v_mul_f32_e32 v133, 0xbfb8aa3b, v133
	v_exp_f32_e32 v130, v130
	v_exp_f32_e32 v131, v131
; __device__ __forceinline__ float siluf(float v) { return v * __builtin_amdgcn_rcpf(1.f + __builtin_amdgcn_exp2f(-1.4426950408889634f * v)); }
; __device__ __forceinline__ float sigmf(float v) { return __builtin_amdgcn_rcpf(1.f + __builtin_amdgcn_exp2f(-1.4426950408889634f * v)); }
; #define G1_STG(mi_, ni_, v_) do { const int r_ = (mi_) * 16 + idx; const f32x4 t_ = (v_); u32x2 pk_; pk_.x = pk2(t_.x, t_.y); pk_.y = pk2(t_.z, t_.w); \
;         *(u32x2*)(wl + r_ * 128 + ((((ni_) * 2 + (kq >> 1)) ^ (r_ & 7)) * 16) + (kq & 1) * 8) = pk_; } while (0)
; __device__ void gemm1_phase(const Params& p, int l, int hb, unsigned char* smem) {
;     ...
;             const float* bg = p.b_gate + l * 3072 + dc0 + lc;
; #pragma unroll
;             for (int mi = 0; mi < 8; ++mi) {
; #pragma unroll
;                 for (int ni = 0; ni < 4; ++ni) {
;                     f32x4 v = acc[mi][ni];
;                     if (mode == 1) { v.x = siluf(v.x); v.y = siluf(v.y); v.z = siluf(v.z); v.w = siluf(v.w); }
;                     else if (mode == 2) { const f32x4 bb = *(const f32x4*)(bg + ni * 16); v.x = sigmf(v.x + bb.x); v.y = sigmf(v.y + bb.y); v.z = sigmf(v.z + bb.z); v.w = sigmf(v.w + bb.w); }
;                     G1_STG(mi, ni, v);
;                 }
	v_exp_f32_e32 v132, v132
	v_exp_f32_e32 v133, v133
	v_add_f32_e32 v130, 1.0, v130
	v_add_f32_e32 v131, 1.0, v131
	v_add_f32_e32 v132, 1.0, v132
	v_add_f32_e32 v133, 1.0, v133
	v_rcp_f32_e32 v130, v130
	v_rcp_f32_e32 v131, v131
	v_rcp_f32_e32 v132, v132
	v_rcp_f32_e32 v133, v133
	s_nop 0
	v_cvt_pk_bf16_f32 v64, v130, v131
	v_cvt_pk_bf16_f32 v65, v132, v133
	ds_write_b64 v139, v[64:65] offset:6144
	v_add_f32_e32 v130, v60, v160
	v_add_f32_e32 v131, v61, v161
	v_add_f32_e32 v132, v62, v162
	v_add_f32_e32 v133, v63, v163
	v_mul_f32_e32 v130, 0xbfb8aa3b, v130
	v_mul_f32_e32 v131, 0xbfb8aa3b, v131
	v_mul_f32_e32 v132, 0xbfb8aa3b, v132
	v_mul_f32_e32 v133, 0xbfb8aa3b, v133
	v_exp_f32_e32 v130, v130
	v_exp_f32_e32 v131, v131
	v_exp_f32_e32 v132, v132
	v_exp_f32_e32 v133, v133
	v_add_f32_e32 v130, 1.0, v130
	v_add_f32_e32 v131, 1.0, v131
	v_add_f32_e32 v132, 1.0, v132
	v_add_f32_e32 v133, 1.0, v133
	v_rcp_f32_e32 v130, v130
	v_rcp_f32_e32 v131, v131
	v_rcp_f32_e32 v132, v132
	v_rcp_f32_e32 v133, v133
	s_nop 0
	v_cvt_pk_bf16_f32 v60, v130, v131
	v_cvt_pk_bf16_f32 v61, v132, v133
	ds_write_b64 v136, v[60:61] offset:8192
	v_add_f32_e32 v130, v56, v164
	v_add_f32_e32 v131, v57, v165
	v_add_f32_e32 v132, v58, v166
	v_add_f32_e32 v133, v59, v167
	v_mul_f32_e32 v130, 0xbfb8aa3b, v130
	v_mul_f32_e32 v131, 0xbfb8aa3b, v131
	v_mul_f32_e32 v132, 0xbfb8aa3b, v132
	v_mul_f32_e32 v133, 0xbfb8aa3b, v133
	v_exp_f32_e32 v130, v130
	v_exp_f32_e32 v131, v131
	v_exp_f32_e32 v132, v132
	v_exp_f32_e32 v133, v133
	v_add_f32_e32 v130, 1.0, v130
	v_add_f32_e32 v131, 1.0, v131
	v_add_f32_e32 v132, 1.0, v132
	v_add_f32_e32 v133, 1.0, v133
	v_rcp_f32_e32 v130, v130
	v_rcp_f32_e32 v131, v131
	v_rcp_f32_e32 v132, v132
	v_rcp_f32_e32 v133, v133
	s_nop 0
	v_cvt_pk_bf16_f32 v56, v130, v131
	v_cvt_pk_bf16_f32 v57, v132, v133
	ds_write_b64 v137, v[56:57] offset:8192
	v_add_f32_e32 v130, v52, v168
	v_add_f32_e32 v131, v53, v169
	v_add_f32_e32 v132, v54, v170
	v_add_f32_e32 v133, v55, v171
	v_mul_f32_e32 v130, 0xbfb8aa3b, v130
	v_mul_f32_e32 v131, 0xbfb8aa3b, v131
	v_mul_f32_e32 v132, 0xbfb8aa3b, v132
	v_mul_f32_e32 v133, 0xbfb8aa3b, v133
	v_exp_f32_e32 v130, v130
	v_exp_f32_e32 v131, v131
	v_exp_f32_e32 v132, v132
	v_exp_f32_e32 v133, v133
	v_add_f32_e32 v130, 1.0, v130
	v_add_f32_e32 v131, 1.0, v131
	v_add_f32_e32 v132, 1.0, v132
	v_add_f32_e32 v133, 1.0, v133
	v_rcp_f32_e32 v130, v130
	v_rcp_f32_e32 v131, v131
	v_rcp_f32_e32 v132, v132
	v_rcp_f32_e32 v133, v133
	s_nop 0
	v_cvt_pk_bf16_f32 v52, v130, v131
	v_cvt_pk_bf16_f32 v53, v132, v133
	ds_write_b64 v138, v[52:53] offset:8192
	v_add_f32_e32 v130, v48, v172
	v_add_f32_e32 v131, v49, v173
	v_add_f32_e32 v132, v50, v174
	v_add_f32_e32 v133, v51, v175
	v_mul_f32_e32 v130, 0xbfb8aa3b, v130
	v_mul_f32_e32 v131, 0xbfb8aa3b, v131
	v_mul_f32_e32 v132, 0xbfb8aa3b, v132
	v_mul_f32_e32 v133, 0xbfb8aa3b, v133
	v_exp_f32_e32 v130, v130
	v_exp_f32_e32 v131, v131
	v_exp_f32_e32 v132, v132
	v_exp_f32_e32 v133, v133
	v_add_f32_e32 v130, 1.0, v130
	v_add_f32_e32 v131, 1.0, v131
	v_add_f32_e32 v132, 1.0, v132
	v_add_f32_e32 v133, 1.0, v133
	v_rcp_f32_e32 v130, v130
	v_rcp_f32_e32 v131, v131
	v_rcp_f32_e32 v132, v132
	v_rcp_f32_e32 v133, v133
	s_nop 0
	v_cvt_pk_bf16_f32 v48, v130, v131
	v_cvt_pk_bf16_f32 v49, v132, v133
	ds_write_b64 v139, v[48:49] offset:8192
	v_add_f32_e32 v130, v44, v160
	v_add_f32_e32 v131, v45, v161
	v_add_f32_e32 v132, v46, v162
	v_add_f32_e32 v133, v47, v163
	v_mul_f32_e32 v130, 0xbfb8aa3b, v130
	v_mul_f32_e32 v131, 0xbfb8aa3b, v131
	v_mul_f32_e32 v132, 0xbfb8aa3b, v132
	v_mul_f32_e32 v133, 0xbfb8aa3b, v133
	v_exp_f32_e32 v130, v130
	v_exp_f32_e32 v131, v131
	v_exp_f32_e32 v132, v132
	v_exp_f32_e32 v133, v133
	v_add_f32_e32 v130, 1.0, v130
	v_add_f32_e32 v131, 1.0, v131
	v_add_f32_e32 v132, 1.0, v132
	v_add_f32_e32 v133, 1.0, v133
	v_rcp_f32_e32 v130, v130
	v_rcp_f32_e32 v131, v131
	v_rcp_f32_e32 v132, v132
	v_rcp_f32_e32 v133, v133
	s_nop 0
	v_cvt_pk_bf16_f32 v44, v130, v131
	v_cvt_pk_bf16_f32 v45, v132, v133
	ds_write_b64 v136, v[44:45] offset:10240
	v_add_f32_e32 v130, v40, v164
	v_add_f32_e32 v131, v41, v165
	v_add_f32_e32 v132, v42, v166
	v_add_f32_e32 v133, v43, v167
	v_mul_f32_e32 v130, 0xbfb8aa3b, v130
	v_mul_f32_e32 v131, 0xbfb8aa3b, v131
	v_mul_f32_e32 v132, 0xbfb8aa3b, v132
	v_mul_f32_e32 v133, 0xbfb8aa3b, v133
	v_exp_f32_e32 v130, v130
	v_exp_f32_e32 v131, v131
	v_exp_f32_e32 v132, v132
	v_exp_f32_e32 v133, v133
	v_add_f32_e32 v130, 1.0, v130
	v_add_f32_e32 v131, 1.0, v131
	v_add_f32_e32 v132, 1.0, v132
	v_add_f32_e32 v133, 1.0, v133
	v_rcp_f32_e32 v130, v130
	v_rcp_f32_e32 v131, v131
	v_rcp_f32_e32 v132, v132
	v_rcp_f32_e32 v133, v133
	s_nop 0
	v_cvt_pk_bf16_f32 v40, v130, v131
	v_cvt_pk_bf16_f32 v41, v132, v133
	ds_write_b64 v137, v[40:41] offset:10240
	v_add_f32_e32 v130, v36, v168
	v_add_f32_e32 v131, v37, v169
	v_add_f32_e32 v132, v38, v170
	v_add_f32_e32 v133, v39, v171
	v_mul_f32_e32 v130, 0xbfb8aa3b, v130
	v_mul_f32_e32 v131, 0xbfb8aa3b, v131
	v_mul_f32_e32 v132, 0xbfb8aa3b, v132
	v_mul_f32_e32 v133, 0xbfb8aa3b, v133
	v_exp_f32_e32 v130, v130
	v_exp_f32_e32 v131, v131
	v_exp_f32_e32 v132, v132
	v_exp_f32_e32 v133, v133
	v_add_f32_e32 v130, 1.0, v130
	v_add_f32_e32 v131, 1.0, v131
	v_add_f32_e32 v132, 1.0, v132
	v_add_f32_e32 v133, 1.0, v133
	v_rcp_f32_e32 v130, v130
	v_rcp_f32_e32 v131, v131
	v_rcp_f32_e32 v132, v132
	v_rcp_f32_e32 v133, v133
	s_nop 0
	v_cvt_pk_bf16_f32 v36, v130, v131
	v_cvt_pk_bf16_f32 v37, v132, v133
	ds_write_b64 v138, v[36:37] offset:10240
	v_add_f32_e32 v130, v32, v172
	v_add_f32_e32 v131, v33, v173
	v_add_f32_e32 v132, v34, v174
	v_add_f32_e32 v133, v35, v175
; __device__ __forceinline__ float siluf(float v) { return v * __builtin_amdgcn_rcpf(1.f + __builtin_amdgcn_exp2f(-1.4426950408889634f * v)); }
; __device__ __forceinline__ float sigmf(float v) { return __builtin_amdgcn_rcpf(1.f + __builtin_amdgcn_exp2f(-1.4426950408889634f * v)); }
; #define G1_STG(mi_, ni_, v_) do { const int r_ = (mi_) * 16 + idx; const f32x4 t_ = (v_); u32x2 pk_; pk_.x = pk2(t_.x, t_.y); pk_.y = pk2(t_.z, t_.w); \
;         *(u32x2*)(wl + r_ * 128 + ((((ni_) * 2 + (kq >> 1)) ^ (r_ & 7)) * 16) + (kq & 1) * 8) = pk_; } while (0)
; __device__ void gemm1_phase(const Params& p, int l, int hb, unsigned char* smem) {
;     ...
;             const float* bg = p.b_gate + l * 3072 + dc0 + lc;
; #pragma unroll
;             for (int mi = 0; mi < 8; ++mi) {
; #pragma unroll
;                 for (int ni = 0; ni < 4; ++ni) {
;                     f32x4 v = acc[mi][ni];
;                     if (mode == 1) { v.x = siluf(v.x); v.y = siluf(v.y); v.z = siluf(v.z); v.w = siluf(v.w); }
;                     else if (mode == 2) { const f32x4 bb = *(const f32x4*)(bg + ni * 16); v.x = sigmf(v.x + bb.x); v.y = sigmf(v.y + bb.y); v.z = sigmf(v.z + bb.z); v.w = sigmf(v.w + bb.w); }
;                     G1_STG(mi, ni, v);
;                 }
;             }
;         }
	v_mul_f32_e32 v130, 0xbfb8aa3b, v130
	v_mul_f32_e32 v131, 0xbfb8aa3b, v131
	v_mul_f32_e32 v132, 0xbfb8aa3b, v132
	v_mul_f32_e32 v133, 0xbfb8aa3b, v133
	v_exp_f32_e32 v130, v130
	v_exp_f32_e32 v131, v131
	v_exp_f32_e32 v132, v132
	v_exp_f32_e32 v133, v133
	v_add_f32_e32 v130, 1.0, v130
	v_add_f32_e32 v131, 1.0, v131
	v_add_f32_e32 v132, 1.0, v132
	v_add_f32_e32 v133, 1.0, v133
	v_rcp_f32_e32 v130, v130
	v_rcp_f32_e32 v131, v131
	v_rcp_f32_e32 v132, v132
	v_rcp_f32_e32 v133, v133
	s_nop 0
	v_cvt_pk_bf16_f32 v32, v130, v131
	v_cvt_pk_bf16_f32 v33, v132, v133
	ds_write_b64 v139, v[32:33] offset:10240
	v_add_f32_e32 v130, v28, v160
	v_add_f32_e32 v131, v29, v161
	v_add_f32_e32 v132, v30, v162
	v_add_f32_e32 v133, v31, v163
	v_mul_f32_e32 v130, 0xbfb8aa3b, v130
	v_mul_f32_e32 v131, 0xbfb8aa3b, v131
	v_mul_f32_e32 v132, 0xbfb8aa3b, v132
	v_mul_f32_e32 v133, 0xbfb8aa3b, v133
	v_exp_f32_e32 v130, v130
	v_exp_f32_e32 v131, v131
	v_exp_f32_e32 v132, v132
	v_exp_f32_e32 v133, v133
	v_add_f32_e32 v130, 1.0, v130
	v_add_f32_e32 v131, 1.0, v131
	v_add_f32_e32 v132, 1.0, v132
	v_add_f32_e32 v133, 1.0, v133
	v_rcp_f32_e32 v130, v130
	v_rcp_f32_e32 v131, v131
	v_rcp_f32_e32 v132, v132
	v_rcp_f32_e32 v133, v133
	s_nop 0
	v_cvt_pk_bf16_f32 v28, v130, v131
	v_cvt_pk_bf16_f32 v29, v132, v133
	ds_write_b64 v136, v[28:29] offset:12288
	v_add_f32_e32 v130, v24, v164
	v_add_f32_e32 v131, v25, v165
	v_add_f32_e32 v132, v26, v166
	v_add_f32_e32 v133, v27, v167
	v_mul_f32_e32 v130, 0xbfb8aa3b, v130
	v_mul_f32_e32 v131, 0xbfb8aa3b, v131
	v_mul_f32_e32 v132, 0xbfb8aa3b, v132
	v_mul_f32_e32 v133, 0xbfb8aa3b, v133
	v_exp_f32_e32 v130, v130
	v_exp_f32_e32 v131, v131
	v_exp_f32_e32 v132, v132
	v_exp_f32_e32 v133, v133
	v_add_f32_e32 v130, 1.0, v130
	v_add_f32_e32 v131, 1.0, v131
	v_add_f32_e32 v132, 1.0, v132
	v_add_f32_e32 v133, 1.0, v133
	v_rcp_f32_e32 v130, v130
	v_rcp_f32_e32 v131, v131
	v_rcp_f32_e32 v132, v132
	v_rcp_f32_e32 v133, v133
	s_nop 0
	v_cvt_pk_bf16_f32 v24, v130, v131
	v_cvt_pk_bf16_f32 v25, v132, v133
	ds_write_b64 v137, v[24:25] offset:12288
	v_add_f32_e32 v130, v20, v168
	v_add_f32_e32 v131, v21, v169
	v_add_f32_e32 v132, v22, v170
	v_add_f32_e32 v133, v23, v171
	v_mul_f32_e32 v130, 0xbfb8aa3b, v130
	v_mul_f32_e32 v131, 0xbfb8aa3b, v131
	v_mul_f32_e32 v132, 0xbfb8aa3b, v132
	v_mul_f32_e32 v133, 0xbfb8aa3b, v133
	v_exp_f32_e32 v130, v130
	v_exp_f32_e32 v131, v131
	v_exp_f32_e32 v132, v132
	v_exp_f32_e32 v133, v133
	v_add_f32_e32 v130, 1.0, v130
	v_add_f32_e32 v131, 1.0, v131
	v_add_f32_e32 v132, 1.0, v132
	v_add_f32_e32 v133, 1.0, v133
	v_rcp_f32_e32 v130, v130
	v_rcp_f32_e32 v131, v131
	v_rcp_f32_e32 v132, v132
	v_rcp_f32_e32 v133, v133
	s_nop 0
	v_cvt_pk_bf16_f32 v20, v130, v131
	v_cvt_pk_bf16_f32 v21, v132, v133
	ds_write_b64 v138, v[20:21] offset:12288
	v_add_f32_e32 v130, v16, v172
	v_add_f32_e32 v131, v17, v173
	v_add_f32_e32 v132, v18, v174
	v_add_f32_e32 v133, v19, v175
	v_mul_f32_e32 v130, 0xbfb8aa3b, v130
	v_mul_f32_e32 v131, 0xbfb8aa3b, v131
	v_mul_f32_e32 v132, 0xbfb8aa3b, v132
	v_mul_f32_e32 v133, 0xbfb8aa3b, v133
	v_exp_f32_e32 v130, v130
	v_exp_f32_e32 v131, v131
	v_exp_f32_e32 v132, v132
	v_exp_f32_e32 v133, v133
	v_add_f32_e32 v130, 1.0, v130
	v_add_f32_e32 v131, 1.0, v131
	v_add_f32_e32 v132, 1.0, v132
	v_add_f32_e32 v133, 1.0, v133
	v_rcp_f32_e32 v130, v130
	v_rcp_f32_e32 v131, v131
	v_rcp_f32_e32 v132, v132
	v_rcp_f32_e32 v133, v133
	s_nop 0
	v_cvt_pk_bf16_f32 v16, v130, v131
	v_cvt_pk_bf16_f32 v17, v132, v133
	ds_write_b64 v139, v[16:17] offset:12288
	v_add_f32_e32 v130, v12, v160
	v_add_f32_e32 v131, v13, v161
	v_add_f32_e32 v132, v14, v162
	v_add_f32_e32 v133, v15, v163
	v_mul_f32_e32 v130, 0xbfb8aa3b, v130
	v_mul_f32_e32 v131, 0xbfb8aa3b, v131
	v_mul_f32_e32 v132, 0xbfb8aa3b, v132
	v_mul_f32_e32 v133, 0xbfb8aa3b, v133
	v_exp_f32_e32 v130, v130
	v_exp_f32_e32 v131, v131
	v_exp_f32_e32 v132, v132
	v_exp_f32_e32 v133, v133
	v_add_f32_e32 v130, 1.0, v130
	v_add_f32_e32 v131, 1.0, v131
	v_add_f32_e32 v132, 1.0, v132
	v_add_f32_e32 v133, 1.0, v133
	v_rcp_f32_e32 v130, v130
	v_rcp_f32_e32 v131, v131
	v_rcp_f32_e32 v132, v132
	v_rcp_f32_e32 v133, v133
	s_nop 0
	v_cvt_pk_bf16_f32 v12, v130, v131
	v_cvt_pk_bf16_f32 v13, v132, v133
	ds_write_b64 v136, v[12:13] offset:14336
	v_add_f32_e32 v130, v8, v164
	v_add_f32_e32 v131, v9, v165
	v_add_f32_e32 v132, v10, v166
	v_add_f32_e32 v133, v11, v167
	v_mul_f32_e32 v130, 0xbfb8aa3b, v130
	v_mul_f32_e32 v131, 0xbfb8aa3b, v131
	v_mul_f32_e32 v132, 0xbfb8aa3b, v132
	v_mul_f32_e32 v133, 0xbfb8aa3b, v133
	v_exp_f32_e32 v130, v130
	v_exp_f32_e32 v131, v131
	v_exp_f32_e32 v132, v132
	v_exp_f32_e32 v133, v133
	v_add_f32_e32 v130, 1.0, v130
	v_add_f32_e32 v131, 1.0, v131
	v_add_f32_e32 v132, 1.0, v132
	v_add_f32_e32 v133, 1.0, v133
	v_rcp_f32_e32 v130, v130
	v_rcp_f32_e32 v131, v131
	v_rcp_f32_e32 v132, v132
	v_rcp_f32_e32 v133, v133
	s_nop 0
	v_cvt_pk_bf16_f32 v8, v130, v131
	v_cvt_pk_bf16_f32 v9, v132, v133
	ds_write_b64 v137, v[8:9] offset:14336
	v_add_f32_e32 v130, v4, v168
	v_add_f32_e32 v131, v5, v169
	v_add_f32_e32 v132, v6, v170
	v_add_f32_e32 v133, v7, v171
	v_mul_f32_e32 v130, 0xbfb8aa3b, v130
	v_mul_f32_e32 v131, 0xbfb8aa3b, v131
	v_mul_f32_e32 v132, 0xbfb8aa3b, v132
	v_mul_f32_e32 v133, 0xbfb8aa3b, v133
	v_exp_f32_e32 v130, v130
	v_exp_f32_e32 v131, v131
	v_exp_f32_e32 v132, v132
	v_exp_f32_e32 v133, v133
	v_add_f32_e32 v130, 1.0, v130
	v_add_f32_e32 v131, 1.0, v131
	v_add_f32_e32 v132, 1.0, v132
	v_add_f32_e32 v133, 1.0, v133
	v_rcp_f32_e32 v130, v130
	v_rcp_f32_e32 v131, v131
	v_rcp_f32_e32 v132, v132
	v_rcp_f32_e32 v133, v133
	s_nop 0
	v_cvt_pk_bf16_f32 v4, v130, v131
	v_cvt_pk_bf16_f32 v5, v132, v133
	ds_write_b64 v138, v[4:5] offset:14336
	v_add_f32_e32 v130, v0, v172
	v_add_f32_e32 v131, v1, v173
	v_add_f32_e32 v132, v2, v174
	v_add_f32_e32 v133, v3, v175
	v_mul_f32_e32 v130, 0xbfb8aa3b, v130
	v_mul_f32_e32 v131, 0xbfb8aa3b, v131
	v_mul_f32_e32 v132, 0xbfb8aa3b, v132
	v_mul_f32_e32 v133, 0xbfb8aa3b, v133
	v_exp_f32_e32 v130, v130
	v_exp_f32_e32 v131, v131
	v_exp_f32_e32 v132, v132
	v_exp_f32_e32 v133, v133
	v_add_f32_e32 v130, 1.0, v130
	v_add_f32_e32 v131, 1.0, v131
	v_add_f32_e32 v132, 1.0, v132
	v_add_f32_e32 v133, 1.0, v133
	v_rcp_f32_e32 v130, v130
	v_rcp_f32_e32 v131, v131
	v_rcp_f32_e32 v132, v132
	v_rcp_f32_e32 v133, v133
	s_nop 0
	v_cvt_pk_bf16_f32 v0, v130, v131
	v_cvt_pk_bf16_f32 v1, v132, v133
	ds_write_b64 v139, v[0:1] offset:14336
.Lg1e_done:
	s_mov_b64 s[36:37], 0
